# GU gemm epilogue rewritten with packed f32 math (re-associated silu*up products, 5 pk ops + 4 trans per output pair); acc zero fill via v_pk_mov_b32; norm_phase pipelined
# speedup vs baseline: 1.0149x; 1.0149x over previous
; template <class Epi, bool FP8>
; __device__ __forceinline__ void gemm_phase(LAS unsigned char* lds, const Gemm g, const SplitOrder& S, const Epi& E) {
;     ...
;     f32x4 acc[2][2][4][2];
; #pragma unroll
;     for (int a = 0; a < 2; ++a)
; #pragma unroll
;         for (int b = 0; b < 2; ++b)
; #pragma unroll
;             for (int m = 0; m < 4; ++m)
; #pragma unroll
;                 for (int n = 0; n < 2; ++n) acc[a][b][m][n] = (f32x4){0.f, 0.f, 0.f, 0.f};
;     ...
;         for (int a = 0; a < 2; ++a)
; #pragma unroll
;             for (int b = 0; b < 2; ++b)
; #pragma unroll
;                 for (int m = 0; m < 4; ++m)
; #pragma unroll
;                     for (int n = 0; n < 2; ++n) acc[a][b][m][n] = (f32x4){0.f, 0.f, 0.f, 0.f};
;         cur = nxt; cA = nA; cB = nB; ++ui;
.LBB0_144:
	s_add_i32 s13, s81, -2
	s_add_u32 s42, s54, 0x80
	s_addc_u32 s43, s55, 0
	s_add_u32 s51, s56, 0x100
	v_mov_b32_e32 v0, 0
	v_mov_b32_e32 v1, 0
	v_pk_mov_b32 v[2:3], v[0:1], v[0:1]
	v_pk_mov_b32 v[4:5], v[0:1], v[0:1]
	v_pk_mov_b32 v[6:7], v[0:1], v[0:1]
	v_pk_mov_b32 v[8:9], v[0:1], v[0:1]
	v_pk_mov_b32 v[10:11], v[0:1], v[0:1]
	v_pk_mov_b32 v[12:13], v[0:1], v[0:1]
	v_pk_mov_b32 v[14:15], v[0:1], v[0:1]
	v_pk_mov_b32 v[18:19], v[0:1], v[0:1]
	v_pk_mov_b32 v[20:21], v[0:1], v[0:1]
	v_pk_mov_b32 v[22:23], v[0:1], v[0:1]
	v_pk_mov_b32 v[24:25], v[0:1], v[0:1]
	v_pk_mov_b32 v[26:27], v[0:1], v[0:1]
	v_pk_mov_b32 v[28:29], v[0:1], v[0:1]
	v_pk_mov_b32 v[30:31], v[0:1], v[0:1]
	v_pk_mov_b32 v[32:33], v[0:1], v[0:1]
	v_pk_mov_b32 v[34:35], v[0:1], v[0:1]
	v_pk_mov_b32 v[36:37], v[0:1], v[0:1]
	v_pk_mov_b32 v[38:39], v[0:1], v[0:1]
	v_pk_mov_b32 v[40:41], v[0:1], v[0:1]
	v_pk_mov_b32 v[42:43], v[0:1], v[0:1]
	v_pk_mov_b32 v[44:45], v[0:1], v[0:1]
	v_pk_mov_b32 v[46:47], v[0:1], v[0:1]
	v_pk_mov_b32 v[48:49], v[0:1], v[0:1]
	v_pk_mov_b32 v[50:51], v[0:1], v[0:1]
	v_pk_mov_b32 v[52:53], v[0:1], v[0:1]
	v_pk_mov_b32 v[54:55], v[0:1], v[0:1]
	v_pk_mov_b32 v[56:57], v[0:1], v[0:1]
	v_pk_mov_b32 v[58:59], v[0:1], v[0:1]
	v_pk_mov_b32 v[60:61], v[0:1], v[0:1]
	v_pk_mov_b32 v[62:63], v[0:1], v[0:1]
	v_pk_mov_b32 v[64:65], v[0:1], v[0:1]
	v_pk_mov_b32 v[66:67], v[0:1], v[0:1]
	v_pk_mov_b32 v[68:69], v[0:1], v[0:1]
	v_pk_mov_b32 v[70:71], v[0:1], v[0:1]
	v_pk_mov_b32 v[72:73], v[0:1], v[0:1]
	v_pk_mov_b32 v[74:75], v[0:1], v[0:1]
	v_pk_mov_b32 v[76:77], v[0:1], v[0:1]
	v_pk_mov_b32 v[78:79], v[0:1], v[0:1]
	v_pk_mov_b32 v[80:81], v[0:1], v[0:1]
	v_pk_mov_b32 v[82:83], v[0:1], v[0:1]
	v_pk_mov_b32 v[84:85], v[0:1], v[0:1]
	v_pk_mov_b32 v[86:87], v[0:1], v[0:1]
	v_pk_mov_b32 v[88:89], v[0:1], v[0:1]
	v_pk_mov_b32 v[90:91], v[0:1], v[0:1]
	v_pk_mov_b32 v[92:93], v[0:1], v[0:1]
	v_pk_mov_b32 v[94:95], v[0:1], v[0:1]
	v_pk_mov_b32 v[96:97], v[0:1], v[0:1]
	v_pk_mov_b32 v[98:99], v[0:1], v[0:1]
	v_pk_mov_b32 v[100:101], v[0:1], v[0:1]
	v_pk_mov_b32 v[102:103], v[0:1], v[0:1]
	v_pk_mov_b32 v[104:105], v[0:1], v[0:1]
	v_pk_mov_b32 v[106:107], v[0:1], v[0:1]
	v_pk_mov_b32 v[108:109], v[0:1], v[0:1]
	v_pk_mov_b32 v[110:111], v[0:1], v[0:1]
	v_pk_mov_b32 v[112:113], v[0:1], v[0:1]
	v_pk_mov_b32 v[114:115], v[0:1], v[0:1]
	v_pk_mov_b32 v[116:117], v[0:1], v[0:1]
	v_pk_mov_b32 v[118:119], v[0:1], v[0:1]
	v_pk_mov_b32 v[120:121], v[0:1], v[0:1]
	v_pk_mov_b32 v[122:123], v[0:1], v[0:1]
	v_pk_mov_b32 v[124:125], v[0:1], v[0:1]
	v_pk_mov_b32 v[126:127], v[0:1], v[0:1]
	v_pk_mov_b32 v[128:129], v[0:1], v[0:1]
	s_addc_u32 s82, s57, 0
	s_mov_b32 s54, 0

; template <class Epi, bool FP8>
; __device__ __forceinline__ void gemm_phase(LAS unsigned char* lds, const Gemm g, const SplitOrder& S, const Epi& E) {
;     ...
;         for (int a = 0; a < 2; ++a)
; #pragma unroll
;             for (int b = 0; b < 2; ++b)
; #pragma unroll
;                 for (int m = 0; m < 4; ++m)
; #pragma unroll
;                     for (int n = 0; n < 2; ++n) acc[a][b][m][n] = (f32x4){0.f, 0.f, 0.f, 0.f};
;         cur = nxt; cA = nA; cB = nB; ++ui;
.LBB0_148:
	v_mov_b32_e32 v0, 0
	v_mov_b32_e32 v1, 0
	v_pk_mov_b32 v[2:3], v[0:1], v[0:1]
	v_pk_mov_b32 v[4:5], v[0:1], v[0:1]
	v_pk_mov_b32 v[6:7], v[0:1], v[0:1]
	v_pk_mov_b32 v[8:9], v[0:1], v[0:1]
	v_pk_mov_b32 v[10:11], v[0:1], v[0:1]
	v_pk_mov_b32 v[12:13], v[0:1], v[0:1]
	v_pk_mov_b32 v[14:15], v[0:1], v[0:1]
	v_pk_mov_b32 v[18:19], v[0:1], v[0:1]
	v_pk_mov_b32 v[20:21], v[0:1], v[0:1]
	v_pk_mov_b32 v[22:23], v[0:1], v[0:1]
	v_pk_mov_b32 v[24:25], v[0:1], v[0:1]
	v_pk_mov_b32 v[26:27], v[0:1], v[0:1]
	v_pk_mov_b32 v[28:29], v[0:1], v[0:1]
	v_pk_mov_b32 v[30:31], v[0:1], v[0:1]
	v_pk_mov_b32 v[32:33], v[0:1], v[0:1]
	v_pk_mov_b32 v[34:35], v[0:1], v[0:1]
	v_pk_mov_b32 v[36:37], v[0:1], v[0:1]
	v_pk_mov_b32 v[38:39], v[0:1], v[0:1]
	v_pk_mov_b32 v[40:41], v[0:1], v[0:1]
	v_pk_mov_b32 v[42:43], v[0:1], v[0:1]
	v_pk_mov_b32 v[44:45], v[0:1], v[0:1]
	v_pk_mov_b32 v[46:47], v[0:1], v[0:1]
	v_pk_mov_b32 v[48:49], v[0:1], v[0:1]
	v_pk_mov_b32 v[50:51], v[0:1], v[0:1]
	v_pk_mov_b32 v[52:53], v[0:1], v[0:1]
	v_pk_mov_b32 v[54:55], v[0:1], v[0:1]
	v_pk_mov_b32 v[56:57], v[0:1], v[0:1]
	v_pk_mov_b32 v[58:59], v[0:1], v[0:1]
	v_pk_mov_b32 v[60:61], v[0:1], v[0:1]
	v_pk_mov_b32 v[62:63], v[0:1], v[0:1]
	v_pk_mov_b32 v[64:65], v[0:1], v[0:1]
	v_pk_mov_b32 v[66:67], v[0:1], v[0:1]
	v_pk_mov_b32 v[68:69], v[0:1], v[0:1]
	v_pk_mov_b32 v[70:71], v[0:1], v[0:1]
	v_pk_mov_b32 v[72:73], v[0:1], v[0:1]
	v_pk_mov_b32 v[74:75], v[0:1], v[0:1]
	v_pk_mov_b32 v[76:77], v[0:1], v[0:1]
	v_pk_mov_b32 v[78:79], v[0:1], v[0:1]
	v_pk_mov_b32 v[80:81], v[0:1], v[0:1]
	v_pk_mov_b32 v[82:83], v[0:1], v[0:1]
	v_pk_mov_b32 v[84:85], v[0:1], v[0:1]
	v_pk_mov_b32 v[86:87], v[0:1], v[0:1]
	v_pk_mov_b32 v[88:89], v[0:1], v[0:1]
	v_pk_mov_b32 v[90:91], v[0:1], v[0:1]
	v_pk_mov_b32 v[92:93], v[0:1], v[0:1]
	v_pk_mov_b32 v[94:95], v[0:1], v[0:1]
	v_pk_mov_b32 v[96:97], v[0:1], v[0:1]
	v_pk_mov_b32 v[98:99], v[0:1], v[0:1]
	v_pk_mov_b32 v[100:101], v[0:1], v[0:1]
	v_pk_mov_b32 v[102:103], v[0:1], v[0:1]
	v_pk_mov_b32 v[104:105], v[0:1], v[0:1]
	v_pk_mov_b32 v[106:107], v[0:1], v[0:1]
	v_pk_mov_b32 v[108:109], v[0:1], v[0:1]
	v_pk_mov_b32 v[110:111], v[0:1], v[0:1]
	v_pk_mov_b32 v[112:113], v[0:1], v[0:1]
	v_pk_mov_b32 v[114:115], v[0:1], v[0:1]
	v_pk_mov_b32 v[116:117], v[0:1], v[0:1]
	v_pk_mov_b32 v[118:119], v[0:1], v[0:1]
	v_pk_mov_b32 v[120:121], v[0:1], v[0:1]
	v_pk_mov_b32 v[122:123], v[0:1], v[0:1]
	v_pk_mov_b32 v[124:125], v[0:1], v[0:1]
	v_pk_mov_b32 v[126:127], v[0:1], v[0:1]
	v_pk_mov_b32 v[128:129], v[0:1], v[0:1]

; template <class Epi, bool FP8>
; __device__ __forceinline__ void gemm_phase(LAS unsigned char* lds, const Gemm g, const SplitOrder& S, const Epi& E) {
;     ...
;     f32x4 acc[2][2][4][2];
; #pragma unroll
;     for (int a = 0; a < 2; ++a)
; #pragma unroll
;         for (int b = 0; b < 2; ++b)
; #pragma unroll
;             for (int m = 0; m < 4; ++m)
; #pragma unroll
;                 for (int n = 0; n < 2; ++n) acc[a][b][m][n] = (f32x4){0.f, 0.f, 0.f, 0.f};
;     ...
;         for (int a = 0; a < 2; ++a)
; #pragma unroll
;             for (int b = 0; b < 2; ++b)
; #pragma unroll
;                 for (int m = 0; m < 4; ++m)
; #pragma unroll
;                     for (int n = 0; n < 2; ++n) acc[a][b][m][n] = (f32x4){0.f, 0.f, 0.f, 0.f};
;         cur = nxt; cA = nA; cB = nB; ++ui;
.LBB0_462:
	s_add_u32 s22, s22, 0x40080
	s_addc_u32 s23, s23, 0
	s_add_u32 s19, s26, 0x100
	v_mov_b32_e32 v0, 0
	v_mov_b32_e32 v1, 0
	v_pk_mov_b32 v[2:3], v[0:1], v[0:1]
	v_pk_mov_b32 v[4:5], v[0:1], v[0:1]
	v_pk_mov_b32 v[6:7], v[0:1], v[0:1]
	v_pk_mov_b32 v[8:9], v[0:1], v[0:1]
	v_pk_mov_b32 v[10:11], v[0:1], v[0:1]
	v_pk_mov_b32 v[12:13], v[0:1], v[0:1]
	v_pk_mov_b32 v[14:15], v[0:1], v[0:1]
	v_pk_mov_b32 v[18:19], v[0:1], v[0:1]
	v_pk_mov_b32 v[20:21], v[0:1], v[0:1]
	v_pk_mov_b32 v[22:23], v[0:1], v[0:1]
	v_pk_mov_b32 v[24:25], v[0:1], v[0:1]
	v_pk_mov_b32 v[26:27], v[0:1], v[0:1]
	v_pk_mov_b32 v[28:29], v[0:1], v[0:1]
	v_pk_mov_b32 v[30:31], v[0:1], v[0:1]
	v_pk_mov_b32 v[32:33], v[0:1], v[0:1]
	v_pk_mov_b32 v[34:35], v[0:1], v[0:1]
	v_pk_mov_b32 v[36:37], v[0:1], v[0:1]
	v_pk_mov_b32 v[38:39], v[0:1], v[0:1]
	v_pk_mov_b32 v[40:41], v[0:1], v[0:1]
	v_pk_mov_b32 v[42:43], v[0:1], v[0:1]
	v_pk_mov_b32 v[44:45], v[0:1], v[0:1]
	v_pk_mov_b32 v[46:47], v[0:1], v[0:1]
	v_pk_mov_b32 v[48:49], v[0:1], v[0:1]
	v_pk_mov_b32 v[50:51], v[0:1], v[0:1]
	v_pk_mov_b32 v[52:53], v[0:1], v[0:1]
	v_pk_mov_b32 v[54:55], v[0:1], v[0:1]
	v_pk_mov_b32 v[56:57], v[0:1], v[0:1]
	v_pk_mov_b32 v[58:59], v[0:1], v[0:1]
	v_pk_mov_b32 v[60:61], v[0:1], v[0:1]
	v_pk_mov_b32 v[62:63], v[0:1], v[0:1]
	v_pk_mov_b32 v[64:65], v[0:1], v[0:1]
	v_pk_mov_b32 v[66:67], v[0:1], v[0:1]
	v_pk_mov_b32 v[68:69], v[0:1], v[0:1]
	v_pk_mov_b32 v[70:71], v[0:1], v[0:1]
	v_pk_mov_b32 v[72:73], v[0:1], v[0:1]
	v_pk_mov_b32 v[74:75], v[0:1], v[0:1]
	v_pk_mov_b32 v[76:77], v[0:1], v[0:1]
	v_pk_mov_b32 v[78:79], v[0:1], v[0:1]
	v_pk_mov_b32 v[80:81], v[0:1], v[0:1]
	v_pk_mov_b32 v[82:83], v[0:1], v[0:1]
	v_pk_mov_b32 v[84:85], v[0:1], v[0:1]
	v_pk_mov_b32 v[86:87], v[0:1], v[0:1]
	v_pk_mov_b32 v[88:89], v[0:1], v[0:1]
	v_pk_mov_b32 v[90:91], v[0:1], v[0:1]
	v_pk_mov_b32 v[92:93], v[0:1], v[0:1]
	v_pk_mov_b32 v[94:95], v[0:1], v[0:1]
	v_pk_mov_b32 v[96:97], v[0:1], v[0:1]
	v_pk_mov_b32 v[98:99], v[0:1], v[0:1]
	v_pk_mov_b32 v[100:101], v[0:1], v[0:1]
	v_pk_mov_b32 v[102:103], v[0:1], v[0:1]
	v_pk_mov_b32 v[104:105], v[0:1], v[0:1]
	v_pk_mov_b32 v[106:107], v[0:1], v[0:1]
	v_pk_mov_b32 v[108:109], v[0:1], v[0:1]
	v_pk_mov_b32 v[110:111], v[0:1], v[0:1]
	v_pk_mov_b32 v[112:113], v[0:1], v[0:1]
	v_pk_mov_b32 v[114:115], v[0:1], v[0:1]
	v_pk_mov_b32 v[116:117], v[0:1], v[0:1]
	v_pk_mov_b32 v[118:119], v[0:1], v[0:1]
	v_pk_mov_b32 v[120:121], v[0:1], v[0:1]
	v_pk_mov_b32 v[122:123], v[0:1], v[0:1]
	v_pk_mov_b32 v[124:125], v[0:1], v[0:1]
	v_pk_mov_b32 v[126:127], v[0:1], v[0:1]
	v_pk_mov_b32 v[128:129], v[0:1], v[0:1]
	s_addc_u32 s25, s27, 0
	s_mov_b32 s42, -2

; template <class Epi, bool FP8>
; __device__ __forceinline__ void gemm_phase(LAS unsigned char* lds, const Gemm g, const SplitOrder& S, const Epi& E) {
;     ...
;     f32x4 acc[2][2][4][2];
; #pragma unroll
;     for (int a = 0; a < 2; ++a)
; #pragma unroll
;         for (int b = 0; b < 2; ++b)
; #pragma unroll
;             for (int m = 0; m < 4; ++m)
; #pragma unroll
;                 for (int n = 0; n < 2; ++n) acc[a][b][m][n] = (f32x4){0.f, 0.f, 0.f, 0.f};
;     ...
;         for (int a = 0; a < 2; ++a)
; #pragma unroll
;             for (int b = 0; b < 2; ++b)
; #pragma unroll
;                 for (int m = 0; m < 4; ++m)
; #pragma unroll
;                     for (int n = 0; n < 2; ++n) acc[a][b][m][n] = (f32x4){0.f, 0.f, 0.f, 0.f};
;         cur = nxt; cA = nA; cB = nB; ++ui;
.LBB0_597:
	s_add_u32 s42, s56, 0x40080
	s_addc_u32 s43, s57, 0
	s_add_u32 s25, s50, 0x100
	v_mov_b32_e32 v0, 0
	v_mov_b32_e32 v1, 0
	v_pk_mov_b32 v[2:3], v[0:1], v[0:1]
	v_pk_mov_b32 v[4:5], v[0:1], v[0:1]
	v_pk_mov_b32 v[6:7], v[0:1], v[0:1]
	v_pk_mov_b32 v[8:9], v[0:1], v[0:1]
	v_pk_mov_b32 v[10:11], v[0:1], v[0:1]
	v_pk_mov_b32 v[12:13], v[0:1], v[0:1]
	v_pk_mov_b32 v[14:15], v[0:1], v[0:1]
	v_pk_mov_b32 v[18:19], v[0:1], v[0:1]
	v_pk_mov_b32 v[20:21], v[0:1], v[0:1]
	v_pk_mov_b32 v[22:23], v[0:1], v[0:1]
	v_pk_mov_b32 v[24:25], v[0:1], v[0:1]
	v_pk_mov_b32 v[26:27], v[0:1], v[0:1]
	v_pk_mov_b32 v[28:29], v[0:1], v[0:1]
	v_pk_mov_b32 v[30:31], v[0:1], v[0:1]
	v_pk_mov_b32 v[32:33], v[0:1], v[0:1]
	v_pk_mov_b32 v[34:35], v[0:1], v[0:1]
	v_pk_mov_b32 v[36:37], v[0:1], v[0:1]
	v_pk_mov_b32 v[38:39], v[0:1], v[0:1]
	v_pk_mov_b32 v[40:41], v[0:1], v[0:1]
	v_pk_mov_b32 v[42:43], v[0:1], v[0:1]
	v_pk_mov_b32 v[44:45], v[0:1], v[0:1]
	v_pk_mov_b32 v[46:47], v[0:1], v[0:1]
	v_pk_mov_b32 v[48:49], v[0:1], v[0:1]
	v_pk_mov_b32 v[50:51], v[0:1], v[0:1]
	v_pk_mov_b32 v[52:53], v[0:1], v[0:1]
	v_pk_mov_b32 v[54:55], v[0:1], v[0:1]
	v_pk_mov_b32 v[56:57], v[0:1], v[0:1]
	v_pk_mov_b32 v[58:59], v[0:1], v[0:1]
	v_pk_mov_b32 v[60:61], v[0:1], v[0:1]
	v_pk_mov_b32 v[62:63], v[0:1], v[0:1]
	v_pk_mov_b32 v[64:65], v[0:1], v[0:1]
	v_pk_mov_b32 v[66:67], v[0:1], v[0:1]
	v_pk_mov_b32 v[68:69], v[0:1], v[0:1]
	v_pk_mov_b32 v[70:71], v[0:1], v[0:1]
	v_pk_mov_b32 v[72:73], v[0:1], v[0:1]
	v_pk_mov_b32 v[74:75], v[0:1], v[0:1]
	v_pk_mov_b32 v[76:77], v[0:1], v[0:1]
	v_pk_mov_b32 v[78:79], v[0:1], v[0:1]
	v_pk_mov_b32 v[80:81], v[0:1], v[0:1]
	v_pk_mov_b32 v[82:83], v[0:1], v[0:1]
	v_pk_mov_b32 v[84:85], v[0:1], v[0:1]
	v_pk_mov_b32 v[86:87], v[0:1], v[0:1]
	v_pk_mov_b32 v[88:89], v[0:1], v[0:1]
	v_pk_mov_b32 v[90:91], v[0:1], v[0:1]
	v_pk_mov_b32 v[92:93], v[0:1], v[0:1]
	v_pk_mov_b32 v[94:95], v[0:1], v[0:1]
	v_pk_mov_b32 v[96:97], v[0:1], v[0:1]
	v_pk_mov_b32 v[98:99], v[0:1], v[0:1]
	v_pk_mov_b32 v[100:101], v[0:1], v[0:1]
	v_pk_mov_b32 v[102:103], v[0:1], v[0:1]
	v_pk_mov_b32 v[104:105], v[0:1], v[0:1]
	v_pk_mov_b32 v[106:107], v[0:1], v[0:1]
	v_pk_mov_b32 v[108:109], v[0:1], v[0:1]
	v_pk_mov_b32 v[110:111], v[0:1], v[0:1]
	v_pk_mov_b32 v[112:113], v[0:1], v[0:1]
	v_pk_mov_b32 v[114:115], v[0:1], v[0:1]
	v_pk_mov_b32 v[116:117], v[0:1], v[0:1]
	v_pk_mov_b32 v[118:119], v[0:1], v[0:1]
	v_pk_mov_b32 v[120:121], v[0:1], v[0:1]
	v_pk_mov_b32 v[122:123], v[0:1], v[0:1]
	v_pk_mov_b32 v[124:125], v[0:1], v[0:1]
	v_pk_mov_b32 v[126:127], v[0:1], v[0:1]
	v_pk_mov_b32 v[128:129], v[0:1], v[0:1]
	s_addc_u32 s27, s51, 0
	s_mov_b32 s35, -2

; template <class Epi, bool FP8>
; __device__ __forceinline__ void gemm_phase(LAS unsigned char* lds, const Gemm g, const SplitOrder& S, const Epi& E) {
;     ...
;     f32x4 acc[2][2][4][2];
; #pragma unroll
;     for (int a = 0; a < 2; ++a)
; #pragma unroll
;         for (int b = 0; b < 2; ++b)
; #pragma unroll
;             for (int m = 0; m < 4; ++m)
; #pragma unroll
;                 for (int n = 0; n < 2; ++n) acc[a][b][m][n] = (f32x4){0.f, 0.f, 0.f, 0.f};
;     ...
;         for (int a = 0; a < 2; ++a)
; #pragma unroll
;             for (int b = 0; b < 2; ++b)
; #pragma unroll
;                 for (int m = 0; m < 4; ++m)
; #pragma unroll
;                     for (int n = 0; n < 2; ++n) acc[a][b][m][n] = (f32x4){0.f, 0.f, 0.f, 0.f};
;         cur = nxt; cA = nA; cB = nB; ++ui;
.LBB0_686:
	s_add_u32 s22, s22, 0x40080
	s_addc_u32 s23, s23, 0
	s_add_u32 s5, s24, 0x100
	v_mov_b32_e32 v0, 0
	v_mov_b32_e32 v1, 0
	v_pk_mov_b32 v[2:3], v[0:1], v[0:1]
	v_pk_mov_b32 v[4:5], v[0:1], v[0:1]
	v_pk_mov_b32 v[6:7], v[0:1], v[0:1]
	v_pk_mov_b32 v[8:9], v[0:1], v[0:1]
	v_pk_mov_b32 v[10:11], v[0:1], v[0:1]
	v_pk_mov_b32 v[12:13], v[0:1], v[0:1]
	v_pk_mov_b32 v[14:15], v[0:1], v[0:1]
	v_pk_mov_b32 v[18:19], v[0:1], v[0:1]
	v_pk_mov_b32 v[20:21], v[0:1], v[0:1]
	v_pk_mov_b32 v[22:23], v[0:1], v[0:1]
	v_pk_mov_b32 v[24:25], v[0:1], v[0:1]
	v_pk_mov_b32 v[26:27], v[0:1], v[0:1]
	v_pk_mov_b32 v[28:29], v[0:1], v[0:1]
	v_pk_mov_b32 v[30:31], v[0:1], v[0:1]
	v_pk_mov_b32 v[32:33], v[0:1], v[0:1]
	v_pk_mov_b32 v[34:35], v[0:1], v[0:1]
	v_pk_mov_b32 v[36:37], v[0:1], v[0:1]
	v_pk_mov_b32 v[38:39], v[0:1], v[0:1]
	v_pk_mov_b32 v[40:41], v[0:1], v[0:1]
	v_pk_mov_b32 v[42:43], v[0:1], v[0:1]
	v_pk_mov_b32 v[44:45], v[0:1], v[0:1]
	v_pk_mov_b32 v[46:47], v[0:1], v[0:1]
	v_pk_mov_b32 v[48:49], v[0:1], v[0:1]
	v_pk_mov_b32 v[50:51], v[0:1], v[0:1]
	v_pk_mov_b32 v[52:53], v[0:1], v[0:1]
	v_pk_mov_b32 v[54:55], v[0:1], v[0:1]
	v_pk_mov_b32 v[56:57], v[0:1], v[0:1]
	v_pk_mov_b32 v[58:59], v[0:1], v[0:1]
	v_pk_mov_b32 v[60:61], v[0:1], v[0:1]
	v_pk_mov_b32 v[62:63], v[0:1], v[0:1]
	v_pk_mov_b32 v[64:65], v[0:1], v[0:1]
	v_pk_mov_b32 v[66:67], v[0:1], v[0:1]
	v_pk_mov_b32 v[68:69], v[0:1], v[0:1]
	v_pk_mov_b32 v[70:71], v[0:1], v[0:1]
	v_pk_mov_b32 v[72:73], v[0:1], v[0:1]
	v_pk_mov_b32 v[74:75], v[0:1], v[0:1]
	v_pk_mov_b32 v[76:77], v[0:1], v[0:1]
	v_pk_mov_b32 v[78:79], v[0:1], v[0:1]
	v_pk_mov_b32 v[80:81], v[0:1], v[0:1]
	v_pk_mov_b32 v[82:83], v[0:1], v[0:1]
	v_pk_mov_b32 v[84:85], v[0:1], v[0:1]
	v_pk_mov_b32 v[86:87], v[0:1], v[0:1]
	v_pk_mov_b32 v[88:89], v[0:1], v[0:1]
	v_pk_mov_b32 v[90:91], v[0:1], v[0:1]
	v_pk_mov_b32 v[92:93], v[0:1], v[0:1]
	v_pk_mov_b32 v[94:95], v[0:1], v[0:1]
	v_pk_mov_b32 v[96:97], v[0:1], v[0:1]
	v_pk_mov_b32 v[98:99], v[0:1], v[0:1]
	v_pk_mov_b32 v[100:101], v[0:1], v[0:1]
	v_pk_mov_b32 v[102:103], v[0:1], v[0:1]
	v_pk_mov_b32 v[104:105], v[0:1], v[0:1]
	v_pk_mov_b32 v[106:107], v[0:1], v[0:1]
	v_pk_mov_b32 v[108:109], v[0:1], v[0:1]
	v_pk_mov_b32 v[110:111], v[0:1], v[0:1]
	v_pk_mov_b32 v[112:113], v[0:1], v[0:1]
	v_pk_mov_b32 v[114:115], v[0:1], v[0:1]
	v_pk_mov_b32 v[116:117], v[0:1], v[0:1]
	v_pk_mov_b32 v[118:119], v[0:1], v[0:1]
	v_pk_mov_b32 v[120:121], v[0:1], v[0:1]
	v_pk_mov_b32 v[122:123], v[0:1], v[0:1]
	v_pk_mov_b32 v[124:125], v[0:1], v[0:1]
	v_pk_mov_b32 v[126:127], v[0:1], v[0:1]
	v_pk_mov_b32 v[128:129], v[0:1], v[0:1]
	s_addc_u32 s19, s25, 0
	s_mov_b32 s34, -2

; template <class Epi, bool FP8>
; __device__ __forceinline__ void gemm_phase(LAS unsigned char* lds, const Gemm g, const SplitOrder& S, const Epi& E) {
;     ...
;     f32x4 acc[2][2][4][2];
; #pragma unroll
;     for (int a = 0; a < 2; ++a)
; #pragma unroll
;         for (int b = 0; b < 2; ++b)
; #pragma unroll
;             for (int m = 0; m < 4; ++m)
; #pragma unroll
;                 for (int n = 0; n < 2; ++n) acc[a][b][m][n] = (f32x4){0.f, 0.f, 0.f, 0.f};
;     ...
;         for (int a = 0; a < 2; ++a)
; #pragma unroll
;             for (int b = 0; b < 2; ++b)
; #pragma unroll
;                 for (int m = 0; m < 4; ++m)
; #pragma unroll
;                     for (int n = 0; n < 2; ++n) acc[a][b][m][n] = (f32x4){0.f, 0.f, 0.f, 0.f};
;         cur = nxt; cA = nA; cB = nB; ++ui;
.LBB0_800:
	s_add_i32 s27, s77, -2
	s_add_u32 s78, s52, 0x100
	v_mov_b32_e32 v18, 0
	v_mov_b32_e32 v19, 0
	v_pk_mov_b32 v[20:21], v[18:19], v[18:19]
	v_pk_mov_b32 v[22:23], v[18:19], v[18:19]
	v_pk_mov_b32 v[24:25], v[18:19], v[18:19]
	v_pk_mov_b32 v[26:27], v[18:19], v[18:19]
	v_pk_mov_b32 v[28:29], v[18:19], v[18:19]
	v_pk_mov_b32 v[30:31], v[18:19], v[18:19]
	v_pk_mov_b32 v[32:33], v[18:19], v[18:19]
	v_pk_mov_b32 v[34:35], v[18:19], v[18:19]
	v_pk_mov_b32 v[36:37], v[18:19], v[18:19]
	v_pk_mov_b32 v[38:39], v[18:19], v[18:19]
	v_pk_mov_b32 v[40:41], v[18:19], v[18:19]
	v_pk_mov_b32 v[42:43], v[18:19], v[18:19]
	v_pk_mov_b32 v[44:45], v[18:19], v[18:19]
	v_pk_mov_b32 v[46:47], v[18:19], v[18:19]
	v_pk_mov_b32 v[48:49], v[18:19], v[18:19]
	v_pk_mov_b32 v[50:51], v[18:19], v[18:19]
	v_pk_mov_b32 v[52:53], v[18:19], v[18:19]
	v_pk_mov_b32 v[54:55], v[18:19], v[18:19]
	v_pk_mov_b32 v[56:57], v[18:19], v[18:19]
	v_pk_mov_b32 v[58:59], v[18:19], v[18:19]
	v_pk_mov_b32 v[60:61], v[18:19], v[18:19]
	v_pk_mov_b32 v[62:63], v[18:19], v[18:19]
	v_pk_mov_b32 v[64:65], v[18:19], v[18:19]
	v_pk_mov_b32 v[66:67], v[18:19], v[18:19]
	v_pk_mov_b32 v[68:69], v[18:19], v[18:19]
	v_pk_mov_b32 v[70:71], v[18:19], v[18:19]
	v_pk_mov_b32 v[72:73], v[18:19], v[18:19]
	v_pk_mov_b32 v[74:75], v[18:19], v[18:19]
	v_pk_mov_b32 v[76:77], v[18:19], v[18:19]
	v_pk_mov_b32 v[78:79], v[18:19], v[18:19]
	v_pk_mov_b32 v[80:81], v[18:19], v[18:19]
	v_pk_mov_b32 v[82:83], v[18:19], v[18:19]
	v_pk_mov_b32 v[84:85], v[18:19], v[18:19]
	v_pk_mov_b32 v[86:87], v[18:19], v[18:19]
	v_pk_mov_b32 v[88:89], v[18:19], v[18:19]
	v_pk_mov_b32 v[90:91], v[18:19], v[18:19]
	v_pk_mov_b32 v[92:93], v[18:19], v[18:19]
	v_pk_mov_b32 v[94:95], v[18:19], v[18:19]
	v_pk_mov_b32 v[96:97], v[18:19], v[18:19]
	v_pk_mov_b32 v[98:99], v[18:19], v[18:19]
	v_pk_mov_b32 v[100:101], v[18:19], v[18:19]
	v_pk_mov_b32 v[102:103], v[18:19], v[18:19]
	v_pk_mov_b32 v[104:105], v[18:19], v[18:19]
	v_pk_mov_b32 v[106:107], v[18:19], v[18:19]
	v_pk_mov_b32 v[108:109], v[18:19], v[18:19]
	v_pk_mov_b32 v[110:111], v[18:19], v[18:19]
	v_pk_mov_b32 v[112:113], v[18:19], v[18:19]
	v_pk_mov_b32 v[114:115], v[18:19], v[18:19]
	v_pk_mov_b32 v[116:117], v[18:19], v[18:19]
	v_pk_mov_b32 v[118:119], v[18:19], v[18:19]
	v_pk_mov_b32 v[120:121], v[18:19], v[18:19]
	v_pk_mov_b32 v[122:123], v[18:19], v[18:19]
	v_pk_mov_b32 v[124:125], v[18:19], v[18:19]
	v_pk_mov_b32 v[126:127], v[18:19], v[18:19]
	v_pk_mov_b32 v[128:129], v[18:19], v[18:19]
	v_pk_mov_b32 v[130:131], v[18:19], v[18:19]
	v_pk_mov_b32 v[132:133], v[18:19], v[18:19]
	v_pk_mov_b32 v[134:135], v[18:19], v[18:19]
	v_pk_mov_b32 v[136:137], v[18:19], v[18:19]
	v_pk_mov_b32 v[138:139], v[18:19], v[18:19]
	v_pk_mov_b32 v[140:141], v[18:19], v[18:19]
	v_pk_mov_b32 v[142:143], v[18:19], v[18:19]
	v_pk_mov_b32 v[144:145], v[18:19], v[18:19]
	s_addc_u32 s79, s53, 0
	s_mov_b32 s42, 0

; template <class Epi, bool FP8>
; __device__ __forceinline__ void gemm_phase(LAS unsigned char* lds, const Gemm g, const SplitOrder& S, const Epi& E) {
;     ...
;         for (int a = 0; a < 2; ++a)
; #pragma unroll
;             for (int b = 0; b < 2; ++b)
; #pragma unroll
;                 for (int m = 0; m < 4; ++m)
; #pragma unroll
;                     for (int n = 0; n < 2; ++n) acc[a][b][m][n] = (f32x4){0.f, 0.f, 0.f, 0.f};
;         cur = nxt; cA = nA; cB = nB; ++ui;
.LBB0_805:
	v_mov_b32_e32 v0, 0
	v_mov_b32_e32 v1, 0
	v_pk_mov_b32 v[2:3], v[0:1], v[0:1]
	v_pk_mov_b32 v[4:5], v[0:1], v[0:1]
	v_pk_mov_b32 v[6:7], v[0:1], v[0:1]
	v_pk_mov_b32 v[8:9], v[0:1], v[0:1]
	v_pk_mov_b32 v[10:11], v[0:1], v[0:1]
	v_pk_mov_b32 v[12:13], v[0:1], v[0:1]
	v_pk_mov_b32 v[14:15], v[0:1], v[0:1]
	v_pk_mov_b32 v[26:27], v[0:1], v[0:1]
	v_pk_mov_b32 v[28:29], v[0:1], v[0:1]
	v_pk_mov_b32 v[30:31], v[0:1], v[0:1]
	v_pk_mov_b32 v[32:33], v[0:1], v[0:1]
	v_pk_mov_b32 v[38:39], v[0:1], v[0:1]
	v_pk_mov_b32 v[40:41], v[0:1], v[0:1]
	v_pk_mov_b32 v[46:47], v[0:1], v[0:1]
	v_pk_mov_b32 v[48:49], v[0:1], v[0:1]
	v_pk_mov_b32 v[54:55], v[0:1], v[0:1]
	v_pk_mov_b32 v[56:57], v[0:1], v[0:1]
	v_pk_mov_b32 v[62:63], v[0:1], v[0:1]
	v_pk_mov_b32 v[64:65], v[0:1], v[0:1]
	v_pk_mov_b32 v[66:67], v[0:1], v[0:1]
	v_pk_mov_b32 v[68:69], v[0:1], v[0:1]
	v_pk_mov_b32 v[70:71], v[0:1], v[0:1]
	v_pk_mov_b32 v[72:73], v[0:1], v[0:1]
	v_pk_mov_b32 v[74:75], v[0:1], v[0:1]
	v_pk_mov_b32 v[76:77], v[0:1], v[0:1]
	v_pk_mov_b32 v[78:79], v[0:1], v[0:1]
	v_pk_mov_b32 v[80:81], v[0:1], v[0:1]
	v_pk_mov_b32 v[82:83], v[0:1], v[0:1]
	v_pk_mov_b32 v[84:85], v[0:1], v[0:1]
	v_pk_mov_b32 v[86:87], v[0:1], v[0:1]
	v_pk_mov_b32 v[88:89], v[0:1], v[0:1]
	v_pk_mov_b32 v[90:91], v[0:1], v[0:1]
	v_pk_mov_b32 v[92:93], v[0:1], v[0:1]
	v_pk_mov_b32 v[94:95], v[0:1], v[0:1]
	v_pk_mov_b32 v[96:97], v[0:1], v[0:1]
	v_pk_mov_b32 v[98:99], v[0:1], v[0:1]
	v_pk_mov_b32 v[100:101], v[0:1], v[0:1]
	v_pk_mov_b32 v[102:103], v[0:1], v[0:1]
	v_pk_mov_b32 v[104:105], v[0:1], v[0:1]
	v_pk_mov_b32 v[110:111], v[0:1], v[0:1]
	v_pk_mov_b32 v[112:113], v[0:1], v[0:1]
	v_pk_mov_b32 v[114:115], v[0:1], v[0:1]
	v_pk_mov_b32 v[116:117], v[0:1], v[0:1]
	v_pk_mov_b32 v[118:119], v[0:1], v[0:1]
	v_pk_mov_b32 v[120:121], v[0:1], v[0:1]
	v_pk_mov_b32 v[122:123], v[0:1], v[0:1]
	v_pk_mov_b32 v[124:125], v[0:1], v[0:1]
	v_pk_mov_b32 v[126:127], v[0:1], v[0:1]
	v_pk_mov_b32 v[128:129], v[0:1], v[0:1]
	v_pk_mov_b32 v[130:131], v[0:1], v[0:1]
	v_pk_mov_b32 v[132:133], v[0:1], v[0:1]
	v_pk_mov_b32 v[134:135], v[0:1], v[0:1]
	v_pk_mov_b32 v[136:137], v[0:1], v[0:1]
	v_pk_mov_b32 v[138:139], v[0:1], v[0:1]
	v_pk_mov_b32 v[140:141], v[0:1], v[0:1]
	v_pk_mov_b32 v[142:143], v[0:1], v[0:1]
	v_pk_mov_b32 v[144:145], v[0:1], v[0:1]
	v_pk_mov_b32 v[174:175], v[0:1], v[0:1]
	v_pk_mov_b32 v[176:177], v[0:1], v[0:1]
	v_pk_mov_b32 v[178:179], v[0:1], v[0:1]
	v_pk_mov_b32 v[180:181], v[0:1], v[0:1]
	v_pk_mov_b32 v[182:183], v[0:1], v[0:1]
	v_pk_mov_b32 v[184:185], v[0:1], v[0:1]

; #define PG8_STAGE(bufoff, gbase, voff) do { _Pragma("unroll") for (int _i = 0; _i < 2; ++_i) \
;         __builtin_amdgcn_global_load_lds((const unsigned*)((const char*)(gbase) + (voff)[_i]), (LAS unsigned*)(lds + (bufoff) + ldsw + _i * 8192), 16, 0, 0); } while (0)
; #define PG8_BAR __builtin_amdgcn_s_barrier()
; template <class Epi, bool FP8>
; __device__ __forceinline__ void gemm_phase(LAS unsigned char* lds, const Gemm g, const SplitOrder& S, const Epi& E) {
;     ...
;     f32x4 acc[2][2][4][2];
; #pragma unroll
;     for (int a = 0; a < 2; ++a)
; #pragma unroll
;         for (int b = 0; b < 2; ++b)
; #pragma unroll
;             for (int m = 0; m < 4; ++m)
; #pragma unroll
;                 for (int n = 0; n < 2; ++n) acc[a][b][m][n] = (f32x4){0.f, 0.f, 0.f, 0.f};
;     ...
;         for (int t = 0; t < nt; t += 2) {
;             const bool last = (t == nt - 2);
;             const char* a1 = cA + (size_t)(t + 1) * kstep;
;             const char* a2 = last ? nA : cA + (size_t)(t + 2) * kstep; const char* b2 = last ? nB : cB + (size_t)(t + 2) * kstep;
;             const char* a3 = a2 + kstep; const char* b3 = b2 + kstep;
;             PG8_LDB(B0, 0, 0); PG8_SCHED; PG8_LDA(At, 0, 0); PG8_STAGE(PG8_SA(1, 1), a1 + hstepA, voffA);
;             PG8_WAIT_L(8); PG8_BAR; PG8_WAIT_L(0); PG8_MMA(0, 0, At, B0); PG8_BAR; PG8_SCHED;
;             PG8_LDB(B1, 0, 1); PG8_STAGE(PG8_SB(0, 0), b2, voffB);
;             PG8_BAR; PG8_WAIT_L(0); PG8_MMA(0, 1, At, B1); PG8_BAR;
;             PG8_LDA(At, 0, 1); PG8_STAGE(PG8_SA(0, 0), a2, voffA);
;             PG8_BAR; PG8_WAIT_L(0); PG8_MMA(1, 0, At, B0); PG8_BAR; PG8_SCHED;
;             PG8_STAGE(PG8_SB(0, 1), b2 + hstepB, voffB);
;             PG8_WAIT_V(6); PG8_BAR; PG8_MMA(1, 1, At, B1); PG8_BAR;
;             PG8_LDB(B0, 1, 0); PG8_SCHED; PG8_LDA(At, 1, 0); PG8_STAGE(PG8_SA(0, 1), a2 + hstepA, voffA);
;             PG8_WAIT_L(8); PG8_BAR; PG8_WAIT_L(0); PG8_MMA(0, 0, At, B0); PG8_BAR; PG8_SCHED;
;             PG8_LDB(B1, 1, 1); PG8_STAGE(PG8_SB(1, 0), b3, voffB);
;             PG8_BAR; PG8_WAIT_L(0); PG8_MMA(0, 1, At, B1); PG8_BAR;
;             PG8_LDA(At, 1, 1); PG8_STAGE(PG8_SA(1, 0), a3, voffA);
;             PG8_BAR; PG8_WAIT_L(0); PG8_MMA(1, 0, At, B0); PG8_BAR; PG8_SCHED;
;             PG8_STAGE(PG8_SB(1, 1), b3 + hstepB, voffB);
;             PG8_WAIT_V(6); PG8_BAR; PG8_MMA(1, 1, At, B1); PG8_BAR;
.LBB0_858:
	s_add_u32 s34, s34, 0x20080
	s_addc_u32 s35, s35, 0
	s_add_u32 s3, s46, 0x100
	v_mov_b32_e32 v18, 0
	v_mov_b32_e32 v19, 0
	v_pk_mov_b32 v[20:21], v[18:19], v[18:19]
	v_pk_mov_b32 v[22:23], v[18:19], v[18:19]
	v_pk_mov_b32 v[24:25], v[18:19], v[18:19]
	v_pk_mov_b32 v[26:27], v[18:19], v[18:19]
	v_pk_mov_b32 v[28:29], v[18:19], v[18:19]
	v_pk_mov_b32 v[30:31], v[18:19], v[18:19]
	v_pk_mov_b32 v[32:33], v[18:19], v[18:19]
	v_pk_mov_b32 v[34:35], v[18:19], v[18:19]
	v_pk_mov_b32 v[36:37], v[18:19], v[18:19]
	v_pk_mov_b32 v[38:39], v[18:19], v[18:19]
	v_pk_mov_b32 v[40:41], v[18:19], v[18:19]
	v_pk_mov_b32 v[42:43], v[18:19], v[18:19]
	v_pk_mov_b32 v[44:45], v[18:19], v[18:19]
	v_pk_mov_b32 v[46:47], v[18:19], v[18:19]
	v_pk_mov_b32 v[48:49], v[18:19], v[18:19]
	v_pk_mov_b32 v[50:51], v[18:19], v[18:19]
	v_pk_mov_b32 v[52:53], v[18:19], v[18:19]
	v_pk_mov_b32 v[54:55], v[18:19], v[18:19]
	v_pk_mov_b32 v[56:57], v[18:19], v[18:19]
	v_pk_mov_b32 v[58:59], v[18:19], v[18:19]
	v_pk_mov_b32 v[60:61], v[18:19], v[18:19]
	v_pk_mov_b32 v[62:63], v[18:19], v[18:19]
	v_pk_mov_b32 v[64:65], v[18:19], v[18:19]
	v_pk_mov_b32 v[66:67], v[18:19], v[18:19]
	v_pk_mov_b32 v[68:69], v[18:19], v[18:19]
	v_pk_mov_b32 v[70:71], v[18:19], v[18:19]
	v_pk_mov_b32 v[72:73], v[18:19], v[18:19]
	v_pk_mov_b32 v[74:75], v[18:19], v[18:19]
	v_pk_mov_b32 v[76:77], v[18:19], v[18:19]
	v_pk_mov_b32 v[78:79], v[18:19], v[18:19]
	v_pk_mov_b32 v[80:81], v[18:19], v[18:19]
	v_pk_mov_b32 v[82:83], v[18:19], v[18:19]
	v_pk_mov_b32 v[84:85], v[18:19], v[18:19]
	v_pk_mov_b32 v[86:87], v[18:19], v[18:19]
	v_pk_mov_b32 v[88:89], v[18:19], v[18:19]
	v_pk_mov_b32 v[90:91], v[18:19], v[18:19]
	v_pk_mov_b32 v[92:93], v[18:19], v[18:19]
	v_pk_mov_b32 v[94:95], v[18:19], v[18:19]
	v_pk_mov_b32 v[96:97], v[18:19], v[18:19]
	v_pk_mov_b32 v[98:99], v[18:19], v[18:19]
	v_pk_mov_b32 v[100:101], v[18:19], v[18:19]
	v_pk_mov_b32 v[102:103], v[18:19], v[18:19]
	v_pk_mov_b32 v[104:105], v[18:19], v[18:19]
	v_pk_mov_b32 v[106:107], v[18:19], v[18:19]
	v_pk_mov_b32 v[108:109], v[18:19], v[18:19]
	v_pk_mov_b32 v[110:111], v[18:19], v[18:19]
	v_pk_mov_b32 v[112:113], v[18:19], v[18:19]
	v_pk_mov_b32 v[114:115], v[18:19], v[18:19]
	v_pk_mov_b32 v[116:117], v[18:19], v[18:19]
	v_pk_mov_b32 v[118:119], v[18:19], v[18:19]
	v_pk_mov_b32 v[120:121], v[18:19], v[18:19]
	v_pk_mov_b32 v[122:123], v[18:19], v[18:19]
	v_pk_mov_b32 v[124:125], v[18:19], v[18:19]
	v_pk_mov_b32 v[126:127], v[18:19], v[18:19]
	v_pk_mov_b32 v[128:129], v[18:19], v[18:19]
	v_pk_mov_b32 v[130:131], v[18:19], v[18:19]
	v_pk_mov_b32 v[132:133], v[18:19], v[18:19]
	v_pk_mov_b32 v[134:135], v[18:19], v[18:19]
	v_pk_mov_b32 v[136:137], v[18:19], v[18:19]
	v_pk_mov_b32 v[138:139], v[18:19], v[18:19]
	v_pk_mov_b32 v[140:141], v[18:19], v[18:19]
	v_pk_mov_b32 v[142:143], v[18:19], v[18:19]
	v_pk_mov_b32 v[144:145], v[18:19], v[18:19]
	s_addc_u32 s5, s47, 0
	s_mov_b32 s19, -2
.LBB0_859:
	s_add_u32 s42, s34, 0xfffe0080
	s_addc_u32 s43, s35, -1
	s_add_i32 s46, 0, 0x10000
	v_add_u32_e32 v12, s46, v182
	ds_read_b128 v[0:3], v12
	ds_read_b128 v[4:7], v12 offset:1024
	ds_read_b128 v[8:11], v12 offset:2048
	ds_read_b128 v[12:15], v12 offset:3072
	s_cmp_eq_u32 s19, 4
	s_cselect_b32 s45, s23, s43
	s_cselect_b32 s44, s22, s42
	s_cselect_b32 s43, s25, s5
	s_cselect_b32 s42, s24, s3
	v_lshl_add_u64 v[174:175], s[34:35], 0, v[170:171]
	s_add_i32 m0, s27, 0xc000
	ds_read_b128 v[202:205], v184
	ds_read_b128 v[206:209], v184 offset:1024
	ds_read_b128 v[210:213], v184 offset:2048
	ds_read_b128 v[214:217], v184 offset:3072
	ds_read_b128 v[218:221], v184 offset:4096
	ds_read_b128 v[222:225], v184 offset:5120
	ds_read_b128 v[226:229], v184 offset:6144
	ds_read_b128 v[230:233], v184 offset:7168
	global_load_lds_dwordx4 v[174:175], off
	v_lshl_add_u64 v[174:175], s[34:35], 0, v[172:173]
	s_add_i32 m0, s27, 0xe000
	s_nop 0
	global_load_lds_dwordx4 v[174:175], off
	s_waitcnt lgkmcnt(8)
	s_barrier
	s_waitcnt lgkmcnt(0)
	s_setprio 1
	s_waitcnt lgkmcnt(0)
	v_mfma_f32_16x16x128_f8f6f4 v[142:145], v[0:7], v[202:209], v[142:145]
	v_mfma_f32_16x16x128_f8f6f4 v[138:141], v[8:15], v[202:209], v[138:141]
	v_mfma_f32_16x16x128_f8f6f4 v[126:129], v[0:7], v[210:217], v[126:129]
	v_mfma_f32_16x16x128_f8f6f4 v[122:125], v[8:15], v[210:217], v[122:125]
	v_mfma_f32_16x16x128_f8f6f4 v[110:113], v[0:7], v[218:225], v[110:113]
	v_mfma_f32_16x16x128_f8f6f4 v[106:109], v[8:15], v[218:225], v[106:109]
	v_mfma_f32_16x16x128_f8f6f4 v[94:97], v[0:7], v[226:233], v[94:97]
	v_mfma_f32_16x16x128_f8f6f4 v[90:93], v[8:15], v[226:233], v[90:93]
	s_setprio 0
	s_barrier
	s_add_i32 s61, 0, 0x14000
	v_add_u32_e32 v174, s61, v182
	s_add_i32 s46, s46, s52
	ds_read_b128 v[234:237], v174
	ds_read_b128 v[238:241], v174 offset:1024
	ds_read_b128 v[242:245], v174 offset:2048
	ds_read_b128 v[246:249], v174 offset:3072
	v_lshl_add_u64 v[174:175], s[42:43], 0, v[16:17]
	s_mov_b32 m0, s46
	v_lshl_add_u64 v[176:177], s[42:43], 0, v[164:165]
	global_load_lds_dwordx4 v[174:175], off
	s_add_i32 m0, s46, 0x2000
	s_nop 0
	global_load_lds_dwordx4 v[176:177], off
	s_barrier
	s_waitcnt lgkmcnt(0)
	s_setprio 1
	s_waitcnt lgkmcnt(0)
	v_mfma_f32_16x16x128_f8f6f4 v[134:137], v[234:241], v[202:209], v[134:137]
	v_mfma_f32_16x16x128_f8f6f4 v[130:133], v[242:249], v[202:209], v[130:133]
	v_mfma_f32_16x16x128_f8f6f4 v[118:121], v[234:241], v[210:217], v[118:121]
	v_mfma_f32_16x16x128_f8f6f4 v[114:117], v[242:249], v[210:217], v[114:117]
	v_mfma_f32_16x16x128_f8f6f4 v[102:105], v[234:241], v[218:225], v[102:105]
	v_mfma_f32_16x16x128_f8f6f4 v[98:101], v[242:249], v[218:225], v[98:101]
	v_mfma_f32_16x16x128_f8f6f4 v[86:89], v[234:241], v[226:233], v[86:89]
	v_mfma_f32_16x16x128_f8f6f4 v[82:85], v[242:249], v[226:233], v[82:85]
	s_setprio 0
	s_mov_b32 m0, s27
	v_lshl_add_u64 v[178:179], s[44:45], 0, v[168:169]
	s_barrier
; #define PG8_STAGE(bufoff, gbase, voff) do { _Pragma("unroll") for (int _i = 0; _i < 2; ++_i) \
;         __builtin_amdgcn_global_load_lds((const unsigned*)((const char*)(gbase) + (voff)[_i]), (LAS unsigned*)(lds + (bufoff) + ldsw + _i * 8192), 16, 0, 0); } while (0)
; #define PG8_WAIT_V(n) asm volatile("s_waitcnt vmcnt(" #n ")" ::: "memory")
; #define PG8_WAIT_L(n) asm volatile("s_waitcnt lgkmcnt(" #n ")" ::: "memory")
; #define PG8_BAR __builtin_amdgcn_s_barrier()
; #define PG8_SCHED __builtin_amdgcn_sched_barrier(0)
; template <class Epi, bool FP8>
; __device__ __forceinline__ void gemm_phase(LAS unsigned char* lds, const Gemm g, const SplitOrder& S, const Epi& E) {
;     ...
;             PG8_LDB(B0, 0, 0); PG8_SCHED; PG8_LDA(At, 0, 0); PG8_STAGE(PG8_SA(1, 1), a1 + hstepA, voffA);
;             PG8_WAIT_L(8); PG8_BAR; PG8_WAIT_L(0); PG8_MMA(0, 0, At, B0); PG8_BAR; PG8_SCHED;
;             PG8_LDB(B1, 0, 1); PG8_STAGE(PG8_SB(0, 0), b2, voffB);
;             PG8_BAR; PG8_WAIT_L(0); PG8_MMA(0, 1, At, B1); PG8_BAR;
;             PG8_LDA(At, 0, 1); PG8_STAGE(PG8_SA(0, 0), a2, voffA);
;             PG8_BAR; PG8_WAIT_L(0); PG8_MMA(1, 0, At, B0); PG8_BAR; PG8_SCHED;
;             PG8_STAGE(PG8_SB(0, 1), b2 + hstepB, voffB);
;             PG8_WAIT_V(6); PG8_BAR; PG8_MMA(1, 1, At, B1); PG8_BAR;
;             PG8_LDB(B0, 1, 0); PG8_SCHED; PG8_LDA(At, 1, 0); PG8_STAGE(PG8_SA(0, 1), a2 + hstepA, voffA);
;             PG8_WAIT_L(8); PG8_BAR; PG8_WAIT_L(0); PG8_MMA(0, 0, At, B0); PG8_BAR; PG8_SCHED;
;             PG8_LDB(B1, 1, 1); PG8_STAGE(PG8_SB(1, 0), b3, voffB);
;             PG8_BAR; PG8_WAIT_L(0); PG8_MMA(0, 1, At, B1); PG8_BAR;
;             PG8_LDA(At, 1, 1); PG8_STAGE(PG8_SA(1, 0), a3, voffA);
;             PG8_BAR; PG8_WAIT_L(0); PG8_MMA(1, 0, At, B0); PG8_BAR; PG8_SCHED;
;             PG8_STAGE(PG8_SB(1, 1), b3 + hstepB, voffB);
;             PG8_WAIT_V(6); PG8_BAR; PG8_MMA(1, 1, At, B1); PG8_BAR;
	ds_read_b128 v[202:205], v184 offset:16384
	ds_read_b128 v[206:209], v184 offset:17408
	ds_read_b128 v[210:213], v184 offset:18432
	ds_read_b128 v[214:217], v184 offset:19456
	ds_read_b128 v[218:221], v184 offset:20480
	ds_read_b128 v[222:225], v184 offset:21504
	ds_read_b128 v[226:229], v184 offset:22528
	ds_read_b128 v[230:233], v184 offset:23552
	global_load_lds_dwordx4 v[178:179], off
	v_lshl_add_u64 v[180:181], s[44:45], 0, v[166:167]
	s_mov_b32 m0, s53
	s_nop 0
	global_load_lds_dwordx4 v[180:181], off
	s_barrier
	s_waitcnt lgkmcnt(0)
	s_setprio 1
	s_waitcnt lgkmcnt(0)
	v_mfma_f32_16x16x128_f8f6f4 v[78:81], v[0:7], v[202:209], v[78:81]
	v_mfma_f32_16x16x128_f8f6f4 v[74:77], v[8:15], v[202:209], v[74:77]
	v_mfma_f32_16x16x128_f8f6f4 v[62:65], v[0:7], v[210:217], v[62:65]
	v_mfma_f32_16x16x128_f8f6f4 v[58:61], v[8:15], v[210:217], v[58:61]
	v_mfma_f32_16x16x128_f8f6f4 v[46:49], v[0:7], v[218:225], v[46:49]
	v_mfma_f32_16x16x128_f8f6f4 v[42:45], v[8:15], v[218:225], v[42:45]
	v_mfma_f32_16x16x128_f8f6f4 v[30:33], v[0:7], v[226:233], v[30:33]
	v_mfma_f32_16x16x128_f8f6f4 v[26:29], v[8:15], v[226:233], v[26:29]
	s_setprio 0
	s_barrier
	s_add_u32 s46, s42, 0x20000
	s_addc_u32 s47, s43, 0
	s_add_i32 s61, s61, s52
	v_lshl_add_u64 v[0:1], s[46:47], 0, v[16:17]
	s_mov_b32 m0, s61
	s_nop 0
	global_load_lds_dwordx4 v[0:1], off
	v_lshl_add_u64 v[0:1], s[46:47], 0, v[164:165]
	s_add_i32 m0, s61, 0x2000
	s_nop 0
	global_load_lds_dwordx4 v[0:1], off
	s_waitcnt vmcnt(6)
	s_barrier
	s_setprio 1
	v_mfma_f32_16x16x128_f8f6f4 v[70:73], v[234:241], v[202:209], v[70:73]
	v_mfma_f32_16x16x128_f8f6f4 v[66:69], v[242:249], v[202:209], v[66:69]
	v_mfma_f32_16x16x128_f8f6f4 v[54:57], v[234:241], v[210:217], v[54:57]
	v_mfma_f32_16x16x128_f8f6f4 v[50:53], v[242:249], v[210:217], v[50:53]
	v_mfma_f32_16x16x128_f8f6f4 v[38:41], v[234:241], v[218:225], v[38:41]
	v_mfma_f32_16x16x128_f8f6f4 v[34:37], v[242:249], v[218:225], v[34:37]
	v_mfma_f32_16x16x128_f8f6f4 v[22:25], v[234:241], v[226:233], v[22:25]
	v_mfma_f32_16x16x128_f8f6f4 v[18:21], v[242:249], v[226:233], v[18:21]
	s_setprio 0
	s_add_i32 s46, 0, 0x18000
	v_add_u32_e32 v12, s46, v182
	s_barrier
	ds_read_b128 v[0:3], v12
	ds_read_b128 v[4:7], v12 offset:1024
	ds_read_b128 v[8:11], v12 offset:2048
	ds_read_b128 v[12:15], v12 offset:3072
	s_add_u32 s44, s44, 0x20000
	s_addc_u32 s45, s45, 0
	s_mov_b32 m0, s54
	v_lshl_add_u64 v[196:197], s[44:45], 0, v[168:169]
	ds_read_b128 v[202:205], v184 offset:32768
	ds_read_b128 v[206:209], v184 offset:33792
	ds_read_b128 v[210:213], v184 offset:34816
	ds_read_b128 v[214:217], v184 offset:35840
	ds_read_b128 v[218:221], v184 offset:36864
	ds_read_b128 v[222:225], v184 offset:37888
	ds_read_b128 v[226:229], v184 offset:38912
	ds_read_b128 v[230:233], v184 offset:39936
	global_load_lds_dwordx4 v[196:197], off
	v_lshl_add_u64 v[196:197], s[44:45], 0, v[166:167]
	s_mov_b32 m0, s55
	s_nop 0
	global_load_lds_dwordx4 v[196:197], off
	s_waitcnt lgkmcnt(8)
	s_barrier
	s_waitcnt lgkmcnt(0)
	s_setprio 1
	s_waitcnt lgkmcnt(0)
	v_mfma_f32_16x16x128_f8f6f4 v[142:145], v[0:7], v[202:209], v[142:145]
	v_mfma_f32_16x16x128_f8f6f4 v[138:141], v[8:15], v[202:209], v[138:141]
	v_mfma_f32_16x16x128_f8f6f4 v[126:129], v[0:7], v[210:217], v[126:129]
	v_mfma_f32_16x16x128_f8f6f4 v[122:125], v[8:15], v[210:217], v[122:125]
	v_mfma_f32_16x16x128_f8f6f4 v[110:113], v[0:7], v[218:225], v[110:113]
	v_mfma_f32_16x16x128_f8f6f4 v[106:109], v[8:15], v[218:225], v[106:109]
	v_mfma_f32_16x16x128_f8f6f4 v[94:97], v[0:7], v[226:233], v[94:97]
	v_mfma_f32_16x16x128_f8f6f4 v[90:93], v[8:15], v[226:233], v[90:93]
	s_setprio 0
	s_barrier
	s_add_i32 s44, 0, 0x1c000
	s_add_i32 s45, s46, s52
	v_add_u32_e32 v185, s44, v182
	v_lshl_add_u64 v[174:175], v[174:175], 0, s[14:15]
	s_mov_b32 m0, s45
	ds_read_b128 v[234:237], v185
	ds_read_b128 v[238:241], v185 offset:1024
	ds_read_b128 v[242:245], v185 offset:2048
	ds_read_b128 v[246:249], v185 offset:3072
	global_load_lds_dwordx4 v[174:175], off
	v_lshl_add_u64 v[174:175], v[176:177], 0, s[14:15]
	s_add_i32 m0, s45, 0x2000
	s_nop 0
	global_load_lds_dwordx4 v[174:175], off
	s_barrier
	s_waitcnt lgkmcnt(0)
	s_setprio 1
	s_waitcnt lgkmcnt(0)
	v_mfma_f32_16x16x128_f8f6f4 v[134:137], v[234:241], v[202:209], v[134:137]
	v_mfma_f32_16x16x128_f8f6f4 v[130:133], v[242:249], v[202:209], v[130:133]
	v_mfma_f32_16x16x128_f8f6f4 v[118:121], v[234:241], v[210:217], v[118:121]
	v_mfma_f32_16x16x128_f8f6f4 v[114:117], v[242:249], v[210:217], v[114:117]
	v_mfma_f32_16x16x128_f8f6f4 v[102:105], v[234:241], v[218:225], v[102:105]
	v_mfma_f32_16x16x128_f8f6f4 v[98:101], v[242:249], v[218:225], v[98:101]
	v_mfma_f32_16x16x128_f8f6f4 v[86:89], v[234:241], v[226:233], v[86:89]
	v_mfma_f32_16x16x128_f8f6f4 v[82:85], v[242:249], v[226:233], v[82:85]
	s_setprio 0
	s_mov_b32 m0, s57
	v_lshl_add_u64 v[174:175], v[178:179], 0, s[14:15]
	s_barrier
	ds_read_b128 v[202:205], v184 offset:49152
	ds_read_b128 v[206:209], v184 offset:50176
	ds_read_b128 v[210:213], v184 offset:51200
	ds_read_b128 v[214:217], v184 offset:52224
	ds_read_b128 v[218:221], v184 offset:53248
	ds_read_b128 v[222:225], v184 offset:54272
	ds_read_b128 v[226:229], v184 offset:55296
	ds_read_b128 v[230:233], v184 offset:56320
	global_load_lds_dwordx4 v[174:175], off
	v_lshl_add_u64 v[174:175], v[180:181], 0, s[14:15]
	s_mov_b32 m0, s58
	s_nop 0
	global_load_lds_dwordx4 v[174:175], off
	s_barrier
; __device__ __forceinline__ float siluf(float x) { return x * __builtin_amdgcn_rcpf(1.0f + __expf(-x)); }
; __device__ __forceinline__ unsigned pk_fp8x4(float a, float b, float c, float d) { int w = 0; w = __builtin_amdgcn_cvt_pk_fp8_f32(clamp448(a), clamp448(b), w, false); w = __builtin_amdgcn_cvt_pk_fp8_f32(clamp448(c), clamp448(d), w, true); return (unsigned)w; }
; #define PG8_WAIT_V(n) asm volatile("s_waitcnt vmcnt(" #n ")" ::: "memory")
; #define PG8_WAIT_L(n) asm volatile("s_waitcnt lgkmcnt(" #n ")" ::: "memory")
; #define PG8_BAR __builtin_amdgcn_s_barrier()
; template <class Epi, bool FP8>
; __device__ __forceinline__ void gemm_phase(LAS unsigned char* lds, const Gemm g, const SplitOrder& S, const Epi& E) {
;     ...
;             PG8_WAIT_V(6); PG8_BAR; PG8_MMA(1, 1, At, B1); PG8_BAR;
;             PG8_LDB(B0, 1, 0); PG8_SCHED; PG8_LDA(At, 1, 0); PG8_STAGE(PG8_SA(0, 1), a2 + hstepA, voffA);
;             PG8_WAIT_L(8); PG8_BAR; PG8_WAIT_L(0); PG8_MMA(0, 0, At, B0); PG8_BAR; PG8_SCHED;
;             PG8_LDB(B1, 1, 1); PG8_STAGE(PG8_SB(1, 0), b3, voffB);
;             PG8_BAR; PG8_WAIT_L(0); PG8_MMA(0, 1, At, B1); PG8_BAR;
;             PG8_LDA(At, 1, 1); PG8_STAGE(PG8_SA(1, 0), a3, voffA);
;             PG8_BAR; PG8_WAIT_L(0); PG8_MMA(1, 0, At, B0); PG8_BAR; PG8_SCHED;
;             PG8_STAGE(PG8_SB(1, 1), b3 + hstepB, voffB);
;             PG8_WAIT_V(6); PG8_BAR; PG8_MMA(1, 1, At, B1); PG8_BAR;
;         }
;     __device__ __forceinline__ void operator()(const f32x4 (&acc)[2][2][4][2], const Unit& u, int wr, int wc, int fr, int fq) const {
;         const int row0 = u.pm * 256 + wr * 64 + fr, col0 = u.pn * 128 + wc * 32 + 8 * fq;
;         constexpr float inv = 1.f / (SC_H * SC_WGU), osc = SC_ACT * inv;
; #pragma unroll
;         for (int ai = 0; ai < 2; ++ai)
; #pragma unroll
;             for (int m = 0; m < 4; ++m) {
;                 const f32x4 g0 = acc[ai][0][m][0] * inv, g1 = acc[ai][0][m][1] * inv, u0 = acc[ai][1][m][0] * osc, u1 = acc[ai][1][m][1] * osc;
;                 u32x2 w;
;                 w.x = pk_fp8x4(siluf(g0[0]) * u0[0], siluf(g0[1]) * u0[1], siluf(g0[2]) * u0[2], siluf(g0[3]) * u0[3]);
;                 w.y = pk_fp8x4(siluf(g1[0]) * u1[0], siluf(g1[1]) * u1[1], siluf(g1[2]) * u1[2], siluf(g1[3]) * u1[3]);
;                 *(u32x2*)(act + (size_t)(row0 + ai * 128 + m * 16) * DFF + col0) = w;
	s_waitcnt lgkmcnt(0)
	s_setprio 1
	s_waitcnt lgkmcnt(0)
	v_mfma_f32_16x16x128_f8f6f4 v[78:81], v[0:7], v[202:209], v[78:81]
	v_mfma_f32_16x16x128_f8f6f4 v[74:77], v[8:15], v[202:209], v[74:77]
	v_mfma_f32_16x16x128_f8f6f4 v[62:65], v[0:7], v[210:217], v[62:65]
	v_mfma_f32_16x16x128_f8f6f4 v[58:61], v[8:15], v[210:217], v[58:61]
	v_mfma_f32_16x16x128_f8f6f4 v[46:49], v[0:7], v[218:225], v[46:49]
	v_mfma_f32_16x16x128_f8f6f4 v[42:45], v[8:15], v[218:225], v[42:45]
	v_mfma_f32_16x16x128_f8f6f4 v[30:33], v[0:7], v[226:233], v[30:33]
	v_mfma_f32_16x16x128_f8f6f4 v[26:29], v[8:15], v[226:233], v[26:29]
	s_setprio 0
	s_barrier
	s_add_u32 s42, s42, 0x20080
	s_addc_u32 s43, s43, 0
	s_add_i32 s44, s44, s52
	v_lshl_add_u64 v[0:1], s[42:43], 0, v[16:17]
	s_mov_b32 m0, s44
	s_nop 0
	global_load_lds_dwordx4 v[0:1], off
	v_lshl_add_u64 v[0:1], s[42:43], 0, v[164:165]
	s_add_i32 m0, s44, 0x2000
	s_nop 0
	global_load_lds_dwordx4 v[0:1], off
	s_waitcnt vmcnt(6)
	s_barrier
	s_setprio 1
	v_mfma_f32_16x16x128_f8f6f4 v[70:73], v[234:241], v[202:209], v[70:73]
	v_mfma_f32_16x16x128_f8f6f4 v[66:69], v[242:249], v[202:209], v[66:69]
	v_mfma_f32_16x16x128_f8f6f4 v[54:57], v[234:241], v[210:217], v[54:57]
	v_mfma_f32_16x16x128_f8f6f4 v[50:53], v[242:249], v[210:217], v[50:53]
	v_mfma_f32_16x16x128_f8f6f4 v[38:41], v[234:241], v[218:225], v[38:41]
	v_mfma_f32_16x16x128_f8f6f4 v[34:37], v[242:249], v[218:225], v[34:37]
	v_mfma_f32_16x16x128_f8f6f4 v[22:25], v[234:241], v[226:233], v[22:25]
	v_mfma_f32_16x16x128_f8f6f4 v[18:21], v[242:249], v[226:233], v[18:21]
	s_setprio 0
	s_add_i32 s19, s19, 2
	s_add_u32 s34, s34, 0x100
	s_addc_u32 s35, s35, 0
	s_add_u32 s3, s3, 0x100
	s_addc_u32 s5, s5, 0
	s_cmp_gt_u32 s19, 5
	s_barrier
	s_cbranch_scc0 .LBB0_859
	s_mov_b32 s42, 0xba38e8a3
	s_mov_b32 s44, 1.0
	s_mov_b32 s46, 0x35b59938
	v_lshl_add_u32 v8, s26, 8, v147
	v_lshl_or_b32 v0, s60, 7, v183
	v_ashrrev_i32_e32 v1, 31, v0
	v_mov_b64_e32 v[2:3], s[0:1]
	v_pk_mul_f32 v[202:203], v[142:143], s[42:43] op_sel_hi:[1,0]
	v_pk_mul_f32 v[204:205], v[144:145], s[42:43] op_sel_hi:[1,0]
	v_pk_mul_f32 v[206:207], v[138:139], s[42:43] op_sel_hi:[1,0]
	v_pk_mul_f32 v[208:209], v[140:141], s[42:43] op_sel_hi:[1,0]
	v_pk_mul_f32 v[210:211], v[142:143], v[134:135]
	v_pk_mul_f32 v[212:213], v[144:145], v[136:137]
	v_pk_mul_f32 v[214:215], v[138:139], v[130:131]
	v_pk_mul_f32 v[216:217], v[140:141], v[132:133]
	v_exp_f32_e32 v202, v202
	v_exp_f32_e32 v203, v203
	v_exp_f32_e32 v204, v204
	v_exp_f32_e32 v205, v205
	v_exp_f32_e32 v206, v206
	v_exp_f32_e32 v207, v207
	v_exp_f32_e32 v208, v208
	v_exp_f32_e32 v209, v209
	v_pk_add_f32 v[202:203], v[202:203], s[44:45] op_sel_hi:[1,0]
	v_pk_add_f32 v[204:205], v[204:205], s[44:45] op_sel_hi:[1,0]
	v_pk_add_f32 v[206:207], v[206:207], s[44:45] op_sel_hi:[1,0]
	v_pk_add_f32 v[208:209], v[208:209], s[44:45] op_sel_hi:[1,0]
	v_rcp_f32_e32 v202, v202
	v_rcp_f32_e32 v203, v203
	v_rcp_f32_e32 v204, v204
	v_rcp_f32_e32 v205, v205
	v_rcp_f32_e32 v206, v206
	v_rcp_f32_e32 v207, v207
	v_rcp_f32_e32 v208, v208
	v_rcp_f32_e32 v209, v209
	v_mad_i64_i32 v[4:5], s[34:35], v8, s39, v[2:3]
	v_pk_mul_f32 v[210:211], v[210:211], v[202:203]
	v_pk_mul_f32 v[212:213], v[212:213], v[204:205]
	v_pk_mul_f32 v[214:215], v[214:215], v[206:207]
	v_pk_mul_f32 v[216:217], v[216:217], v[208:209]
	v_pk_mul_f32 v[210:211], v[210:211], s[46:47] op_sel_hi:[1,0]
	v_pk_mul_f32 v[212:213], v[212:213], s[46:47] op_sel_hi:[1,0]
	v_pk_mul_f32 v[214:215], v[214:215], s[46:47] op_sel_hi:[1,0]
	v_pk_mul_f32 v[216:217], v[216:217], s[46:47] op_sel_hi:[1,0]
	v_med3_f32 v210, v210, s17, v190
	v_med3_f32 v211, v211, s17, v190
	v_med3_f32 v212, v212, s17, v190
	v_med3_f32 v213, v213, s17, v190
	v_med3_f32 v214, v214, s17, v190
	v_med3_f32 v215, v215, s17, v190
	v_med3_f32 v216, v216, s17, v190
	v_med3_f32 v217, v217, s17, v190
	v_cvt_pk_fp8_f32 v6, v210, v211
	v_cvt_pk_fp8_f32 v7, v214, v215
	s_nop 0
	v_cvt_pk_fp8_f32 v6, v212, v213 op_sel:[0,0,1]
	v_cvt_pk_fp8_f32 v7, v216, v217 op_sel:[0,0,1]
	v_lshl_add_u64 v[4:5], v[4:5], 0, v[0:1]
	global_store_dwordx2 v[4:5], v[6:7], off
	v_pk_mul_f32 v[202:203], v[126:127], s[42:43] op_sel_hi:[1,0]
	v_pk_mul_f32 v[204:205], v[128:129], s[42:43] op_sel_hi:[1,0]
	v_pk_mul_f32 v[206:207], v[122:123], s[42:43] op_sel_hi:[1,0]
	v_pk_mul_f32 v[208:209], v[124:125], s[42:43] op_sel_hi:[1,0]
	v_pk_mul_f32 v[210:211], v[126:127], v[118:119]
	v_pk_mul_f32 v[212:213], v[128:129], v[120:121]
	v_pk_mul_f32 v[214:215], v[122:123], v[114:115]
	v_pk_mul_f32 v[216:217], v[124:125], v[116:117]
	v_exp_f32_e32 v202, v202
	v_exp_f32_e32 v203, v203
	v_exp_f32_e32 v204, v204
	v_exp_f32_e32 v205, v205
	v_exp_f32_e32 v206, v206
	v_exp_f32_e32 v207, v207
	v_exp_f32_e32 v208, v208
	v_exp_f32_e32 v209, v209
	v_pk_add_f32 v[202:203], v[202:203], s[44:45] op_sel_hi:[1,0]
	v_pk_add_f32 v[204:205], v[204:205], s[44:45] op_sel_hi:[1,0]
	v_pk_add_f32 v[206:207], v[206:207], s[44:45] op_sel_hi:[1,0]
	v_pk_add_f32 v[208:209], v[208:209], s[44:45] op_sel_hi:[1,0]
	v_rcp_f32_e32 v202, v202
	v_rcp_f32_e32 v203, v203
	v_rcp_f32_e32 v204, v204
	v_rcp_f32_e32 v205, v205
	v_rcp_f32_e32 v206, v206
	v_rcp_f32_e32 v207, v207
	v_rcp_f32_e32 v208, v208
	v_rcp_f32_e32 v209, v209
	v_add_u32_e32 v12, 0x10, v8
	v_pk_mul_f32 v[210:211], v[210:211], v[202:203]
	v_pk_mul_f32 v[212:213], v[212:213], v[204:205]
	v_pk_mul_f32 v[214:215], v[214:215], v[206:207]
	v_pk_mul_f32 v[216:217], v[216:217], v[208:209]
	v_mad_i64_i32 v[12:13], s[34:35], v12, s39, v[2:3]
	v_pk_mul_f32 v[210:211], v[210:211], s[46:47] op_sel_hi:[1,0]
	v_pk_mul_f32 v[212:213], v[212:213], s[46:47] op_sel_hi:[1,0]
; __device__ __forceinline__ float siluf(float x) { return x * __builtin_amdgcn_rcpf(1.0f + __expf(-x)); }
; __device__ __forceinline__ unsigned pk_fp8x4(float a, float b, float c, float d) { int w = 0; w = __builtin_amdgcn_cvt_pk_fp8_f32(clamp448(a), clamp448(b), w, false); w = __builtin_amdgcn_cvt_pk_fp8_f32(clamp448(c), clamp448(d), w, true); return (unsigned)w; }
;     __device__ __forceinline__ void operator()(const f32x4 (&acc)[2][2][4][2], const Unit& u, int wr, int wc, int fr, int fq) const {
;     ...
;         for (int ai = 0; ai < 2; ++ai)
; #pragma unroll
;             for (int m = 0; m < 4; ++m) {
;                 const f32x4 g0 = acc[ai][0][m][0] * inv, g1 = acc[ai][0][m][1] * inv, u0 = acc[ai][1][m][0] * osc, u1 = acc[ai][1][m][1] * osc;
;                 u32x2 w;
;                 w.x = pk_fp8x4(siluf(g0[0]) * u0[0], siluf(g0[1]) * u0[1], siluf(g0[2]) * u0[2], siluf(g0[3]) * u0[3]);
;                 w.y = pk_fp8x4(siluf(g1[0]) * u1[0], siluf(g1[1]) * u1[1], siluf(g1[2]) * u1[2], siluf(g1[3]) * u1[3]);
;                 *(u32x2*)(act + (size_t)(row0 + ai * 128 + m * 16) * DFF + col0) = w;
	v_pk_mul_f32 v[214:215], v[214:215], s[46:47] op_sel_hi:[1,0]
	v_pk_mul_f32 v[216:217], v[216:217], s[46:47] op_sel_hi:[1,0]
	v_med3_f32 v210, v210, s17, v190
	v_med3_f32 v211, v211, s17, v190
	v_med3_f32 v212, v212, s17, v190
	v_med3_f32 v213, v213, s17, v190
	v_med3_f32 v214, v214, s17, v190
	v_med3_f32 v215, v215, s17, v190
	v_med3_f32 v216, v216, s17, v190
	v_med3_f32 v217, v217, s17, v190
	v_cvt_pk_fp8_f32 v10, v210, v211
	v_cvt_pk_fp8_f32 v11, v214, v215
	s_nop 0
	v_cvt_pk_fp8_f32 v10, v212, v213 op_sel:[0,0,1]
	v_cvt_pk_fp8_f32 v11, v216, v217 op_sel:[0,0,1]
	v_lshl_add_u64 v[12:13], v[12:13], 0, v[0:1]
	global_store_dwordx2 v[12:13], v[10:11], off
	v_pk_mul_f32 v[202:203], v[110:111], s[42:43] op_sel_hi:[1,0]
	v_pk_mul_f32 v[204:205], v[112:113], s[42:43] op_sel_hi:[1,0]
	v_pk_mul_f32 v[206:207], v[106:107], s[42:43] op_sel_hi:[1,0]
	v_pk_mul_f32 v[208:209], v[108:109], s[42:43] op_sel_hi:[1,0]
	v_pk_mul_f32 v[210:211], v[110:111], v[102:103]
	v_pk_mul_f32 v[212:213], v[112:113], v[104:105]
	v_pk_mul_f32 v[214:215], v[106:107], v[98:99]
	v_pk_mul_f32 v[216:217], v[108:109], v[100:101]
	v_exp_f32_e32 v202, v202
	v_exp_f32_e32 v203, v203
	v_exp_f32_e32 v204, v204
	v_exp_f32_e32 v205, v205
	v_exp_f32_e32 v206, v206
	v_exp_f32_e32 v207, v207
	v_exp_f32_e32 v208, v208
	v_exp_f32_e32 v209, v209
	v_pk_add_f32 v[202:203], v[202:203], s[44:45] op_sel_hi:[1,0]
	v_pk_add_f32 v[204:205], v[204:205], s[44:45] op_sel_hi:[1,0]
	v_pk_add_f32 v[206:207], v[206:207], s[44:45] op_sel_hi:[1,0]
	v_pk_add_f32 v[208:209], v[208:209], s[44:45] op_sel_hi:[1,0]
	v_rcp_f32_e32 v202, v202
	v_rcp_f32_e32 v203, v203
	v_rcp_f32_e32 v204, v204
	v_rcp_f32_e32 v205, v205
	v_rcp_f32_e32 v206, v206
	v_rcp_f32_e32 v207, v207
	v_rcp_f32_e32 v208, v208
	v_rcp_f32_e32 v209, v209
	v_add_u32_e32 v4, 0x20, v8
	v_pk_mul_f32 v[210:211], v[210:211], v[202:203]
	v_pk_mul_f32 v[212:213], v[212:213], v[204:205]
	v_pk_mul_f32 v[214:215], v[214:215], v[206:207]
	v_pk_mul_f32 v[216:217], v[216:217], v[208:209]
	v_mad_i64_i32 v[4:5], s[34:35], v4, s39, v[2:3]
	v_pk_mul_f32 v[210:211], v[210:211], s[46:47] op_sel_hi:[1,0]
	v_pk_mul_f32 v[212:213], v[212:213], s[46:47] op_sel_hi:[1,0]
	v_pk_mul_f32 v[214:215], v[214:215], s[46:47] op_sel_hi:[1,0]
	v_pk_mul_f32 v[216:217], v[216:217], s[46:47] op_sel_hi:[1,0]
	v_med3_f32 v210, v210, s17, v190
	v_med3_f32 v211, v211, s17, v190
	v_med3_f32 v212, v212, s17, v190
	v_med3_f32 v213, v213, s17, v190
	v_med3_f32 v214, v214, s17, v190
	v_med3_f32 v215, v215, s17, v190
	v_med3_f32 v216, v216, s17, v190
	v_med3_f32 v217, v217, s17, v190
	v_cvt_pk_fp8_f32 v6, v210, v211
	v_cvt_pk_fp8_f32 v7, v214, v215
	s_nop 0
	v_cvt_pk_fp8_f32 v6, v212, v213 op_sel:[0,0,1]
	v_cvt_pk_fp8_f32 v7, v216, v217 op_sel:[0,0,1]
	v_lshl_add_u64 v[4:5], v[4:5], 0, v[0:1]
	global_store_dwordx2 v[4:5], v[6:7], off
	v_pk_mul_f32 v[202:203], v[94:95], s[42:43] op_sel_hi:[1,0]
	v_pk_mul_f32 v[204:205], v[96:97], s[42:43] op_sel_hi:[1,0]
	v_pk_mul_f32 v[206:207], v[90:91], s[42:43] op_sel_hi:[1,0]
	v_pk_mul_f32 v[208:209], v[92:93], s[42:43] op_sel_hi:[1,0]
	v_pk_mul_f32 v[210:211], v[94:95], v[86:87]
	v_pk_mul_f32 v[212:213], v[96:97], v[88:89]
	v_pk_mul_f32 v[214:215], v[90:91], v[82:83]
	v_pk_mul_f32 v[216:217], v[92:93], v[84:85]
	v_exp_f32_e32 v202, v202
	v_exp_f32_e32 v203, v203
	v_exp_f32_e32 v204, v204
	v_exp_f32_e32 v205, v205
	v_exp_f32_e32 v206, v206
	v_exp_f32_e32 v207, v207
	v_exp_f32_e32 v208, v208
	v_exp_f32_e32 v209, v209
	v_pk_add_f32 v[202:203], v[202:203], s[44:45] op_sel_hi:[1,0]
	v_pk_add_f32 v[204:205], v[204:205], s[44:45] op_sel_hi:[1,0]
	v_pk_add_f32 v[206:207], v[206:207], s[44:45] op_sel_hi:[1,0]
	v_pk_add_f32 v[208:209], v[208:209], s[44:45] op_sel_hi:[1,0]
	v_rcp_f32_e32 v202, v202
	v_rcp_f32_e32 v203, v203
	v_rcp_f32_e32 v204, v204
	v_rcp_f32_e32 v205, v205
	v_rcp_f32_e32 v206, v206
	v_rcp_f32_e32 v207, v207
	v_rcp_f32_e32 v208, v208
	v_rcp_f32_e32 v209, v209
	v_add_u32_e32 v12, 0x30, v8
	v_pk_mul_f32 v[210:211], v[210:211], v[202:203]
	v_pk_mul_f32 v[212:213], v[212:213], v[204:205]
	v_pk_mul_f32 v[214:215], v[214:215], v[206:207]
	v_pk_mul_f32 v[216:217], v[216:217], v[208:209]
	v_mad_i64_i32 v[12:13], s[34:35], v12, s39, v[2:3]
	v_pk_mul_f32 v[210:211], v[210:211], s[46:47] op_sel_hi:[1,0]
	v_pk_mul_f32 v[212:213], v[212:213], s[46:47] op_sel_hi:[1,0]
	v_pk_mul_f32 v[214:215], v[214:215], s[46:47] op_sel_hi:[1,0]
	v_pk_mul_f32 v[216:217], v[216:217], s[46:47] op_sel_hi:[1,0]
	v_med3_f32 v210, v210, s17, v190
	v_med3_f32 v211, v211, s17, v190
	v_med3_f32 v212, v212, s17, v190
	v_med3_f32 v213, v213, s17, v190
	v_med3_f32 v214, v214, s17, v190
	v_med3_f32 v215, v215, s17, v190
	v_med3_f32 v216, v216, s17, v190
	v_med3_f32 v217, v217, s17, v190
	v_cvt_pk_fp8_f32 v10, v210, v211
	v_cvt_pk_fp8_f32 v11, v214, v215
	s_nop 0
	v_cvt_pk_fp8_f32 v10, v212, v213 op_sel:[0,0,1]
	v_cvt_pk_fp8_f32 v11, v216, v217 op_sel:[0,0,1]
	v_lshl_add_u64 v[12:13], v[12:13], 0, v[0:1]
	global_store_dwordx2 v[12:13], v[10:11], off
	v_pk_mul_f32 v[202:203], v[78:79], s[42:43] op_sel_hi:[1,0]
	v_pk_mul_f32 v[204:205], v[80:81], s[42:43] op_sel_hi:[1,0]
	v_pk_mul_f32 v[206:207], v[74:75], s[42:43] op_sel_hi:[1,0]
	v_pk_mul_f32 v[208:209], v[76:77], s[42:43] op_sel_hi:[1,0]
	v_pk_mul_f32 v[210:211], v[78:79], v[70:71]
	v_pk_mul_f32 v[212:213], v[80:81], v[72:73]
	v_pk_mul_f32 v[214:215], v[74:75], v[66:67]
	v_pk_mul_f32 v[216:217], v[76:77], v[68:69]
	v_exp_f32_e32 v202, v202
	v_exp_f32_e32 v203, v203
	v_exp_f32_e32 v204, v204
	v_exp_f32_e32 v205, v205
	v_exp_f32_e32 v206, v206
	v_exp_f32_e32 v207, v207
	v_exp_f32_e32 v208, v208
	v_exp_f32_e32 v209, v209
; __device__ __forceinline__ float siluf(float x) { return x * __builtin_amdgcn_rcpf(1.0f + __expf(-x)); }
; __device__ __forceinline__ unsigned pk_fp8x4(float a, float b, float c, float d) { int w = 0; w = __builtin_amdgcn_cvt_pk_fp8_f32(clamp448(a), clamp448(b), w, false); w = __builtin_amdgcn_cvt_pk_fp8_f32(clamp448(c), clamp448(d), w, true); return (unsigned)w; }
;     __device__ __forceinline__ void operator()(const f32x4 (&acc)[2][2][4][2], const Unit& u, int wr, int wc, int fr, int fq) const {
;     ...
;         for (int ai = 0; ai < 2; ++ai)
; #pragma unroll
;             for (int m = 0; m < 4; ++m) {
;                 const f32x4 g0 = acc[ai][0][m][0] * inv, g1 = acc[ai][0][m][1] * inv, u0 = acc[ai][1][m][0] * osc, u1 = acc[ai][1][m][1] * osc;
;                 u32x2 w;
;                 w.x = pk_fp8x4(siluf(g0[0]) * u0[0], siluf(g0[1]) * u0[1], siluf(g0[2]) * u0[2], siluf(g0[3]) * u0[3]);
;                 w.y = pk_fp8x4(siluf(g1[0]) * u1[0], siluf(g1[1]) * u1[1], siluf(g1[2]) * u1[2], siluf(g1[3]) * u1[3]);
;                 *(u32x2*)(act + (size_t)(row0 + ai * 128 + m * 16) * DFF + col0) = w;
	v_pk_add_f32 v[202:203], v[202:203], s[44:45] op_sel_hi:[1,0]
	v_pk_add_f32 v[204:205], v[204:205], s[44:45] op_sel_hi:[1,0]
	v_pk_add_f32 v[206:207], v[206:207], s[44:45] op_sel_hi:[1,0]
	v_pk_add_f32 v[208:209], v[208:209], s[44:45] op_sel_hi:[1,0]
	v_rcp_f32_e32 v202, v202
	v_rcp_f32_e32 v203, v203
	v_rcp_f32_e32 v204, v204
	v_rcp_f32_e32 v205, v205
	v_rcp_f32_e32 v206, v206
	v_rcp_f32_e32 v207, v207
	v_rcp_f32_e32 v208, v208
	v_rcp_f32_e32 v209, v209
	v_add_u32_e32 v4, 0x80, v8
	v_pk_mul_f32 v[210:211], v[210:211], v[202:203]
	v_pk_mul_f32 v[212:213], v[212:213], v[204:205]
	v_pk_mul_f32 v[214:215], v[214:215], v[206:207]
	v_pk_mul_f32 v[216:217], v[216:217], v[208:209]
	v_mad_i64_i32 v[4:5], s[34:35], v4, s39, v[2:3]
	v_pk_mul_f32 v[210:211], v[210:211], s[46:47] op_sel_hi:[1,0]
	v_pk_mul_f32 v[212:213], v[212:213], s[46:47] op_sel_hi:[1,0]
	v_pk_mul_f32 v[214:215], v[214:215], s[46:47] op_sel_hi:[1,0]
	v_pk_mul_f32 v[216:217], v[216:217], s[46:47] op_sel_hi:[1,0]
	v_med3_f32 v210, v210, s17, v190
	v_med3_f32 v211, v211, s17, v190
	v_med3_f32 v212, v212, s17, v190
	v_med3_f32 v213, v213, s17, v190
	v_med3_f32 v214, v214, s17, v190
	v_med3_f32 v215, v215, s17, v190
	v_med3_f32 v216, v216, s17, v190
	v_med3_f32 v217, v217, s17, v190
	v_cvt_pk_fp8_f32 v6, v210, v211
	v_cvt_pk_fp8_f32 v7, v214, v215
	s_nop 0
	v_cvt_pk_fp8_f32 v6, v212, v213 op_sel:[0,0,1]
	v_cvt_pk_fp8_f32 v7, v216, v217 op_sel:[0,0,1]
	v_lshl_add_u64 v[4:5], v[4:5], 0, v[0:1]
	global_store_dwordx2 v[4:5], v[6:7], off
	v_pk_mul_f32 v[202:203], v[62:63], s[42:43] op_sel_hi:[1,0]
	v_pk_mul_f32 v[204:205], v[64:65], s[42:43] op_sel_hi:[1,0]
	v_pk_mul_f32 v[206:207], v[58:59], s[42:43] op_sel_hi:[1,0]
	v_pk_mul_f32 v[208:209], v[60:61], s[42:43] op_sel_hi:[1,0]
	v_pk_mul_f32 v[210:211], v[62:63], v[54:55]
	v_pk_mul_f32 v[212:213], v[64:65], v[56:57]
	v_pk_mul_f32 v[214:215], v[58:59], v[50:51]
	v_pk_mul_f32 v[216:217], v[60:61], v[52:53]
	v_exp_f32_e32 v202, v202
	v_exp_f32_e32 v203, v203
	v_exp_f32_e32 v204, v204
	v_exp_f32_e32 v205, v205
	v_exp_f32_e32 v206, v206
	v_exp_f32_e32 v207, v207
	v_exp_f32_e32 v208, v208
	v_exp_f32_e32 v209, v209
	v_pk_add_f32 v[202:203], v[202:203], s[44:45] op_sel_hi:[1,0]
	v_pk_add_f32 v[204:205], v[204:205], s[44:45] op_sel_hi:[1,0]
	v_pk_add_f32 v[206:207], v[206:207], s[44:45] op_sel_hi:[1,0]
	v_pk_add_f32 v[208:209], v[208:209], s[44:45] op_sel_hi:[1,0]
	v_rcp_f32_e32 v202, v202
	v_rcp_f32_e32 v203, v203
	v_rcp_f32_e32 v204, v204
	v_rcp_f32_e32 v205, v205
	v_rcp_f32_e32 v206, v206
	v_rcp_f32_e32 v207, v207
	v_rcp_f32_e32 v208, v208
	v_rcp_f32_e32 v209, v209
	v_add_u32_e32 v12, 0x90, v8
	v_pk_mul_f32 v[210:211], v[210:211], v[202:203]
	v_pk_mul_f32 v[212:213], v[212:213], v[204:205]
	v_pk_mul_f32 v[214:215], v[214:215], v[206:207]
	v_pk_mul_f32 v[216:217], v[216:217], v[208:209]
	v_mad_i64_i32 v[12:13], s[34:35], v12, s39, v[2:3]
	v_pk_mul_f32 v[210:211], v[210:211], s[46:47] op_sel_hi:[1,0]
	v_pk_mul_f32 v[212:213], v[212:213], s[46:47] op_sel_hi:[1,0]
	v_pk_mul_f32 v[214:215], v[214:215], s[46:47] op_sel_hi:[1,0]
	v_pk_mul_f32 v[216:217], v[216:217], s[46:47] op_sel_hi:[1,0]
	v_med3_f32 v210, v210, s17, v190
	v_med3_f32 v211, v211, s17, v190
	v_med3_f32 v212, v212, s17, v190
	v_med3_f32 v213, v213, s17, v190
	v_med3_f32 v214, v214, s17, v190
	v_med3_f32 v215, v215, s17, v190
	v_med3_f32 v216, v216, s17, v190
	v_med3_f32 v217, v217, s17, v190
	v_cvt_pk_fp8_f32 v10, v210, v211
	v_cvt_pk_fp8_f32 v11, v214, v215
	s_nop 0
	v_cvt_pk_fp8_f32 v10, v212, v213 op_sel:[0,0,1]
	v_cvt_pk_fp8_f32 v11, v216, v217 op_sel:[0,0,1]
	v_lshl_add_u64 v[12:13], v[12:13], 0, v[0:1]
	global_store_dwordx2 v[12:13], v[10:11], off
	v_pk_mul_f32 v[202:203], v[46:47], s[42:43] op_sel_hi:[1,0]
	v_pk_mul_f32 v[204:205], v[48:49], s[42:43] op_sel_hi:[1,0]
	v_pk_mul_f32 v[206:207], v[42:43], s[42:43] op_sel_hi:[1,0]
	v_pk_mul_f32 v[208:209], v[44:45], s[42:43] op_sel_hi:[1,0]
	v_pk_mul_f32 v[210:211], v[46:47], v[38:39]
	v_pk_mul_f32 v[212:213], v[48:49], v[40:41]
	v_pk_mul_f32 v[214:215], v[42:43], v[34:35]
	v_pk_mul_f32 v[216:217], v[44:45], v[36:37]
	v_exp_f32_e32 v202, v202
	v_exp_f32_e32 v203, v203
	v_exp_f32_e32 v204, v204
; __device__ __forceinline__ float siluf(float x) { return x * __builtin_amdgcn_rcpf(1.0f + __expf(-x)); }
; __device__ __forceinline__ unsigned pk_fp8x4(float a, float b, float c, float d) { int w = 0; w = __builtin_amdgcn_cvt_pk_fp8_f32(clamp448(a), clamp448(b), w, false); w = __builtin_amdgcn_cvt_pk_fp8_f32(clamp448(c), clamp448(d), w, true); return (unsigned)w; }
; #define PG8_WAIT_V(n) asm volatile("s_waitcnt vmcnt(" #n ")" ::: "memory")
; #define PG8_BAR __builtin_amdgcn_s_barrier()
; template <class Epi, bool FP8>
; __device__ __forceinline__ void gemm_phase(LAS unsigned char* lds, const Gemm g, const SplitOrder& S, const Epi& E) {
;     ...
;         E(acc, cur, wr, wc, fr, fq);
;         if (!has_next) break;
; #pragma unroll
;         for (int a = 0; a < 2; ++a)
; #pragma unroll
;             for (int b = 0; b < 2; ++b)
; #pragma unroll
;                 for (int m = 0; m < 4; ++m)
; #pragma unroll
;                     for (int n = 0; n < 2; ++n) acc[a][b][m][n] = (f32x4){0.f, 0.f, 0.f, 0.f};
;         cur = nxt; cA = nA; cB = nB; ++ui;
;     }
;     PG8_WAIT_V(0);
;     if (wr == 0) PG8_BAR;
;     PG8_BAR;
;     __device__ __forceinline__ void operator()(const f32x4 (&acc)[2][2][4][2], const Unit& u, int wr, int wc, int fr, int fq) const {
;     ...
;             for (int m = 0; m < 4; ++m) {
;                 const f32x4 g0 = acc[ai][0][m][0] * inv, g1 = acc[ai][0][m][1] * inv, u0 = acc[ai][1][m][0] * osc, u1 = acc[ai][1][m][1] * osc;
;                 u32x2 w;
;                 w.x = pk_fp8x4(siluf(g0[0]) * u0[0], siluf(g0[1]) * u0[1], siluf(g0[2]) * u0[2], siluf(g0[3]) * u0[3]);
;                 w.y = pk_fp8x4(siluf(g1[0]) * u1[0], siluf(g1[1]) * u1[1], siluf(g1[2]) * u1[2], siluf(g1[3]) * u1[3]);
;                 *(u32x2*)(act + (size_t)(row0 + ai * 128 + m * 16) * DFF + col0) = w;
	v_exp_f32_e32 v205, v205
	v_exp_f32_e32 v206, v206
	v_exp_f32_e32 v207, v207
	v_exp_f32_e32 v208, v208
	v_exp_f32_e32 v209, v209
	v_pk_add_f32 v[202:203], v[202:203], s[44:45] op_sel_hi:[1,0]
	v_pk_add_f32 v[204:205], v[204:205], s[44:45] op_sel_hi:[1,0]
	v_pk_add_f32 v[206:207], v[206:207], s[44:45] op_sel_hi:[1,0]
	v_pk_add_f32 v[208:209], v[208:209], s[44:45] op_sel_hi:[1,0]
	v_rcp_f32_e32 v202, v202
	v_rcp_f32_e32 v203, v203
	v_rcp_f32_e32 v204, v204
	v_rcp_f32_e32 v205, v205
	v_rcp_f32_e32 v206, v206
	v_rcp_f32_e32 v207, v207
	v_rcp_f32_e32 v208, v208
	v_rcp_f32_e32 v209, v209
	v_add_u32_e32 v4, 0xa0, v8
	v_pk_mul_f32 v[210:211], v[210:211], v[202:203]
	v_pk_mul_f32 v[212:213], v[212:213], v[204:205]
	v_pk_mul_f32 v[214:215], v[214:215], v[206:207]
	v_pk_mul_f32 v[216:217], v[216:217], v[208:209]
	v_mad_i64_i32 v[4:5], s[34:35], v4, s39, v[2:3]
	v_pk_mul_f32 v[210:211], v[210:211], s[46:47] op_sel_hi:[1,0]
	v_pk_mul_f32 v[212:213], v[212:213], s[46:47] op_sel_hi:[1,0]
	v_pk_mul_f32 v[214:215], v[214:215], s[46:47] op_sel_hi:[1,0]
	v_pk_mul_f32 v[216:217], v[216:217], s[46:47] op_sel_hi:[1,0]
	v_med3_f32 v210, v210, s17, v190
	v_med3_f32 v211, v211, s17, v190
	v_med3_f32 v212, v212, s17, v190
	v_med3_f32 v213, v213, s17, v190
	v_med3_f32 v214, v214, s17, v190
	v_med3_f32 v215, v215, s17, v190
	v_med3_f32 v216, v216, s17, v190
	v_med3_f32 v217, v217, s17, v190
	v_cvt_pk_fp8_f32 v6, v210, v211
	v_cvt_pk_fp8_f32 v7, v214, v215
	s_nop 0
	v_cvt_pk_fp8_f32 v6, v212, v213 op_sel:[0,0,1]
	v_cvt_pk_fp8_f32 v7, v216, v217 op_sel:[0,0,1]
	v_lshl_add_u64 v[4:5], v[4:5], 0, v[0:1]
	global_store_dwordx2 v[4:5], v[6:7], off
	v_pk_mul_f32 v[202:203], v[30:31], s[42:43] op_sel_hi:[1,0]
	v_pk_mul_f32 v[204:205], v[32:33], s[42:43] op_sel_hi:[1,0]
	v_pk_mul_f32 v[206:207], v[26:27], s[42:43] op_sel_hi:[1,0]
	v_pk_mul_f32 v[208:209], v[28:29], s[42:43] op_sel_hi:[1,0]
	v_pk_mul_f32 v[210:211], v[30:31], v[22:23]
	v_pk_mul_f32 v[212:213], v[32:33], v[24:25]
	v_pk_mul_f32 v[214:215], v[26:27], v[18:19]
	v_pk_mul_f32 v[216:217], v[28:29], v[20:21]
	v_exp_f32_e32 v202, v202
	v_exp_f32_e32 v203, v203
	v_exp_f32_e32 v204, v204
	v_exp_f32_e32 v205, v205
	v_exp_f32_e32 v206, v206
	v_exp_f32_e32 v207, v207
	v_exp_f32_e32 v208, v208
	v_exp_f32_e32 v209, v209
	v_pk_add_f32 v[202:203], v[202:203], s[44:45] op_sel_hi:[1,0]
	v_pk_add_f32 v[204:205], v[204:205], s[44:45] op_sel_hi:[1,0]
	v_pk_add_f32 v[206:207], v[206:207], s[44:45] op_sel_hi:[1,0]
	v_pk_add_f32 v[208:209], v[208:209], s[44:45] op_sel_hi:[1,0]
	v_rcp_f32_e32 v202, v202
	v_rcp_f32_e32 v203, v203
	v_rcp_f32_e32 v204, v204
	v_rcp_f32_e32 v205, v205
	v_rcp_f32_e32 v206, v206
	v_rcp_f32_e32 v207, v207
	v_rcp_f32_e32 v208, v208
	v_rcp_f32_e32 v209, v209
	v_add_u32_e32 v12, 0xb0, v8
	v_pk_mul_f32 v[210:211], v[210:211], v[202:203]
	v_pk_mul_f32 v[212:213], v[212:213], v[204:205]
	v_pk_mul_f32 v[214:215], v[214:215], v[206:207]
	v_pk_mul_f32 v[216:217], v[216:217], v[208:209]
	v_mad_i64_i32 v[12:13], s[34:35], v12, s39, v[2:3]
	v_pk_mul_f32 v[210:211], v[210:211], s[46:47] op_sel_hi:[1,0]
	v_pk_mul_f32 v[212:213], v[212:213], s[46:47] op_sel_hi:[1,0]
	v_pk_mul_f32 v[214:215], v[214:215], s[46:47] op_sel_hi:[1,0]
	v_pk_mul_f32 v[216:217], v[216:217], s[46:47] op_sel_hi:[1,0]
	v_med3_f32 v210, v210, s17, v190
	v_med3_f32 v211, v211, s17, v190
	v_med3_f32 v212, v212, s17, v190
	v_med3_f32 v213, v213, s17, v190
	v_med3_f32 v214, v214, s17, v190
	v_med3_f32 v215, v215, s17, v190
	v_med3_f32 v216, v216, s17, v190
	v_med3_f32 v217, v217, s17, v190
	v_cvt_pk_fp8_f32 v10, v210, v211
	v_cvt_pk_fp8_f32 v11, v214, v215
	s_nop 0
	v_cvt_pk_fp8_f32 v10, v212, v213 op_sel:[0,0,1]
	v_cvt_pk_fp8_f32 v11, v216, v217 op_sel:[0,0,1]
	v_lshl_add_u64 v[12:13], v[12:13], 0, v[0:1]
	global_store_dwordx2 v[12:13], v[10:11], off
	s_and_b64 vcc, exec, s[40:41]
	s_mov_b32 s60, s18
	s_mov_b32 s26, s4
	s_mov_b64 s[46:47], s[24:25]
	s_mov_b64 s[34:35], s[22:23]
	s_cbranch_vccz .LBB0_848
	s_waitcnt vmcnt(0)
	v_readlane_b32 s58, v254, 54
	s_cmpk_gt_u32 s13, 0xff
	v_readlane_b32 s59, v254, 55
	v_readlane_b32 s60, v254, 56
	v_readlane_b32 s61, v254, 57
	s_cbranch_scc1 .LBB0_863
	s_barrier
